# dead-instruction cleanup: unused V base and half-loop flag in NSA tile headers, selected-branch mask constant once per tile, unused clamped row indices in RWKV prep tails
# baseline (speedup 1.0000x reference)
.LBB0_283:
	s_add_i32 s13, s12, 1
	s_min_i32 s4, s13, s10
	s_lshl_b32 s96, s4, 6
	s_lshl_b64 s[6:7], s[96:97], 7
	s_lshl_b64 s[4:5], s[96:97], 1
	v_lshl_add_u64 v[2:3], v[190:191], 0, s[6:7]
	global_load_dwordx4 v[8:11], v[2:3], off offset:-2048
	s_nop 0
	global_load_dwordx4 v[4:7], v[2:3], off offset:2048
	v_lshl_add_u64 v[2:3], v[162:163], 0, s[4:5]
	v_lshl_add_u64 v[48:49], v[164:165], 0, s[4:5]
	global_load_dwordx4 v[12:15], v[2:3], off
	global_load_dwordx4 v[112:115], v[48:49], off
	s_and_b32 s14, s12, 1
	s_mul_i32 s4, s14, 0x4800
	v_lshrrev_b64 v[2:3], s12, v[128:129]
	s_lshl_b32 s15, s12, 6
	v_and_b32_e32 v0, 1, v2
	s_or_b32 s5, s15, 63
	v_or_b32_e32 v3, s4, v131
	v_cmp_eq_u64_e64 s[38:39], 0, v[0:1]
	s_cmp_gt_i32 s5, s8
	s_cbranch_scc1 .LBB0_289
	v_mad_u32_u24 v0, v217, s37, v3
	v_lshl_add_u32 v215, v156, 1, v3
	ds_read_b128 v[220:223], v0
	ds_read_b128 v[236:239], v0 offset:4608
	ds_read_b128 v[224:227], v0 offset:32
	ds_read_b128 v[240:243], v0 offset:4640
	ds_read_b128 v[228:231], v0 offset:64
	ds_read_b128 v[244:247], v0 offset:4672
	ds_read_b128 v[232:235], v0 offset:96
	ds_read_b128 v[248:251], v0 offset:4704
	ds_read_b128 v[64:67], v215 offset:9216
	ds_read_b128 v[68:71], v215 offset:13824
	ds_read_b128 v[72:75], v215 offset:9248
	ds_read_b128 v[76:79], v215 offset:13856
	s_waitcnt lgkmcnt(11)
	v_mfma_f32_32x32x16_bf16 v[80:95], v[220:223], v[96:99], 0
	s_waitcnt lgkmcnt(10)
	v_mfma_f32_32x32x16_bf16 v[48:63], v[236:239], v[96:99], 0
	s_waitcnt lgkmcnt(9)
	v_mfma_f32_32x32x16_bf16 v[80:95], v[224:227], v[100:103], v[80:95]
	s_waitcnt lgkmcnt(8)
	v_mfma_f32_32x32x16_bf16 v[48:63], v[240:243], v[100:103], v[48:63]
	s_waitcnt lgkmcnt(7)
	v_mfma_f32_32x32x16_bf16 v[80:95], v[228:231], v[104:107], v[80:95]
	s_waitcnt lgkmcnt(6)
	v_mfma_f32_32x32x16_bf16 v[48:63], v[244:247], v[104:107], v[48:63]
	s_waitcnt lgkmcnt(5)
	v_mfma_f32_32x32x16_bf16 v[80:95], v[232:235], v[108:111], v[80:95]
	s_waitcnt lgkmcnt(4)
	v_mfma_f32_32x32x16_bf16 v[48:63], v[248:251], v[108:111], v[48:63]
	ds_read_b128 v[220:223], v215 offset:9280
	ds_read_b128 v[224:227], v215 offset:13888
	ds_read_b128 v[228:231], v215 offset:9312
	ds_read_b128 v[232:235], v215 offset:13920
	s_nop 7
	v_max3_f32 v0, v80, v81, v82
	v_max3_f32 v2, v88, v89, v90
	v_max3_f32 v0, v0, v83, v84
	v_max3_f32 v2, v2, v91, v92
	v_max3_f32 v0, v0, v85, v86
	v_max3_f32 v2, v2, v93, v94
	v_max3_f32 v0, v0, v87, v95
	v_max_f32_e32 v0, v0, v2
	v_max3_f32 v175, v48, v49, v50
	v_max3_f32 v214, v56, v57, v58
	v_max3_f32 v175, v175, v51, v52
	v_max3_f32 v214, v214, v59, v60
	v_max3_f32 v175, v175, v53, v54
	v_max3_f32 v214, v214, v61, v62
	v_max3_f32 v175, v175, v55, v63
	v_max_f32_e32 v175, v175, v214
	v_cmp_gt_f32_e32 vcc, v0, v219
	s_andn2_b64 vcc, vcc, s[38:39]
	s_cmp_eq_u64 vcc, 0
	s_cbranch_scc1 .Lnsw_keep0
	v_cndmask_b32_e64 v0, v0, v202, s[38:39]
	s_nop 0
	ds_bpermute_b32 v2, v119, v0
	s_waitcnt lgkmcnt(0)
	v_max_f32_e32 v0, v0, v2
	v_max_f32_e32 v173, v167, v0
	v_sub_f32_e32 v0, v167, v173
	v_exp_f32_e32 v0, v0
	v_mov_b32_e32 v167, v173
	v_add_f32_e32 v219, 0x41200000, v173
	v_mul_f32_e32 v169, v169, v0
	v_pk_mul_f32 v[46:47], v[46:47], v[0:1] op_sel_hi:[1,0]
	v_pk_mul_f32 v[44:45], v[44:45], v[0:1] op_sel_hi:[1,0]
	v_pk_mul_f32 v[42:43], v[42:43], v[0:1] op_sel_hi:[1,0]
	v_pk_mul_f32 v[40:41], v[40:41], v[0:1] op_sel_hi:[1,0]
	v_pk_mul_f32 v[38:39], v[38:39], v[0:1] op_sel_hi:[1,0]
	v_pk_mul_f32 v[36:37], v[36:37], v[0:1] op_sel_hi:[1,0]
	v_pk_mul_f32 v[34:35], v[34:35], v[0:1] op_sel_hi:[1,0]
	v_pk_mul_f32 v[32:33], v[32:33], v[0:1] op_sel_hi:[1,0]
	v_pk_mul_f32 v[30:31], v[30:31], v[0:1] op_sel_hi:[1,0]
	v_pk_mul_f32 v[28:29], v[28:29], v[0:1] op_sel_hi:[1,0]
	v_pk_mul_f32 v[26:27], v[26:27], v[0:1] op_sel_hi:[1,0]
	v_pk_mul_f32 v[24:25], v[24:25], v[0:1] op_sel_hi:[1,0]
	v_pk_mul_f32 v[22:23], v[22:23], v[0:1] op_sel_hi:[1,0]
	v_pk_mul_f32 v[20:21], v[20:21], v[0:1] op_sel_hi:[1,0]
	v_pk_mul_f32 v[18:19], v[18:19], v[0:1] op_sel_hi:[1,0]
	v_pk_mul_f32 v[16:17], v[16:17], v[0:1] op_sel_hi:[1,0]
.Lnsw_keep0:
	v_cndmask_b32_e64 v174, v167, v206, s[38:39]
	v_sub_f32_e32 v80, v80, v174
	v_exp_f32_e32 v80, v80
	v_sub_f32_e32 v81, v81, v174
	v_exp_f32_e32 v81, v81
	v_sub_f32_e32 v82, v82, v174
	v_exp_f32_e32 v82, v82
	v_add_f32_e32 v213, v81, v80
	v_sub_f32_e32 v83, v83, v174
	v_exp_f32_e32 v83, v83
	v_add_f32_e32 v213, v82, v213
	v_cvt_pk_bf16_f32 v176, v80, v81
	v_sub_f32_e32 v84, v84, v174
	v_exp_f32_e32 v84, v84
	v_add_f32_e32 v213, v83, v213
	v_sub_f32_e32 v85, v85, v174
	v_exp_f32_e32 v85, v85
	v_add_f32_e32 v213, v84, v213
	v_cvt_pk_bf16_f32 v177, v82, v83
	v_sub_f32_e32 v86, v86, v174
	v_exp_f32_e32 v86, v86
	v_add_f32_e32 v213, v85, v213
	v_sub_f32_e32 v87, v87, v174
	v_exp_f32_e32 v87, v87
	v_add_f32_e32 v213, v86, v213
	v_cvt_pk_bf16_f32 v178, v84, v85
	v_sub_f32_e32 v88, v88, v174
	v_exp_f32_e32 v88, v88
	v_add_f32_e32 v213, v87, v213
	v_sub_f32_e32 v89, v89, v174
	v_exp_f32_e32 v89, v89
	v_add_f32_e32 v213, v88, v213
	v_cvt_pk_bf16_f32 v179, v86, v87
	v_sub_f32_e32 v90, v90, v174
	v_exp_f32_e32 v90, v90
	v_add_f32_e32 v213, v89, v213
	s_waitcnt lgkmcnt(7)
	v_mfma_f32_32x32x16_bf16 v[32:47], v[64:67], v[176:179], v[32:47]
	s_waitcnt lgkmcnt(6)
	v_mfma_f32_32x32x16_bf16 v[16:31], v[68:71], v[176:179], v[16:31]
	v_sub_f32_e32 v91, v91, v174
	v_exp_f32_e32 v91, v91
	v_add_f32_e32 v213, v90, v213
	v_cvt_pk_bf16_f32 v180, v88, v89
	v_sub_f32_e32 v92, v92, v174
	v_exp_f32_e32 v92, v92
	v_add_f32_e32 v213, v91, v213
	v_sub_f32_e32 v93, v93, v174
	v_exp_f32_e32 v93, v93
	v_add_f32_e32 v213, v92, v213
	v_cvt_pk_bf16_f32 v181, v90, v91
	v_sub_f32_e32 v94, v94, v174
	v_exp_f32_e32 v94, v94
	v_add_f32_e32 v213, v93, v213
	v_sub_f32_e32 v95, v95, v174
	v_exp_f32_e32 v95, v95
	v_add_f32_e32 v213, v94, v213
	v_cvt_pk_bf16_f32 v182, v92, v93
	v_add_f32_e32 v213, v95, v213
	v_cvt_pk_bf16_f32 v183, v94, v95
	v_add_f32_e32 v169, v169, v213
	s_nop 0
	s_waitcnt lgkmcnt(5)
	v_mfma_f32_32x32x16_bf16 v[32:47], v[72:75], v[180:183], v[32:47]
	s_waitcnt lgkmcnt(4)
	v_mfma_f32_32x32x16_bf16 v[16:31], v[76:79], v[180:183], v[16:31]
	v_cmp_gt_f32_e32 vcc, v175, v219
	s_andn2_b64 vcc, vcc, s[38:39]
	s_cmp_eq_u64 vcc, 0
	s_cbranch_scc1 .Lnsw_keep1
	v_cndmask_b32_e64 v175, v175, v202, s[38:39]
	s_nop 0
	ds_bpermute_b32 v214, v119, v175
	s_waitcnt lgkmcnt(0)
	v_max_f32_e32 v175, v175, v214
	v_max_f32_e32 v173, v167, v175
	v_sub_f32_e32 v0, v167, v173
	v_exp_f32_e32 v0, v0
	v_mov_b32_e32 v167, v173
	v_add_f32_e32 v219, 0x41200000, v173
	v_mul_f32_e32 v169, v169, v0
	v_cndmask_b32_e64 v174, v167, v206, s[38:39]
	v_pk_mul_f32 v[46:47], v[46:47], v[0:1] op_sel_hi:[1,0]
	v_pk_mul_f32 v[44:45], v[44:45], v[0:1] op_sel_hi:[1,0]
	v_pk_mul_f32 v[42:43], v[42:43], v[0:1] op_sel_hi:[1,0]
	v_pk_mul_f32 v[40:41], v[40:41], v[0:1] op_sel_hi:[1,0]
	v_pk_mul_f32 v[38:39], v[38:39], v[0:1] op_sel_hi:[1,0]
	v_pk_mul_f32 v[36:37], v[36:37], v[0:1] op_sel_hi:[1,0]
	v_pk_mul_f32 v[34:35], v[34:35], v[0:1] op_sel_hi:[1,0]
	v_pk_mul_f32 v[32:33], v[32:33], v[0:1] op_sel_hi:[1,0]
	v_pk_mul_f32 v[30:31], v[30:31], v[0:1] op_sel_hi:[1,0]
	v_pk_mul_f32 v[28:29], v[28:29], v[0:1] op_sel_hi:[1,0]
	v_pk_mul_f32 v[26:27], v[26:27], v[0:1] op_sel_hi:[1,0]
	v_pk_mul_f32 v[24:25], v[24:25], v[0:1] op_sel_hi:[1,0]
	v_pk_mul_f32 v[22:23], v[22:23], v[0:1] op_sel_hi:[1,0]
	v_pk_mul_f32 v[20:21], v[20:21], v[0:1] op_sel_hi:[1,0]
	v_pk_mul_f32 v[18:19], v[18:19], v[0:1] op_sel_hi:[1,0]
	v_pk_mul_f32 v[16:17], v[16:17], v[0:1] op_sel_hi:[1,0]
.Lnsw_keep1:
	v_sub_f32_e32 v48, v48, v174
	v_exp_f32_e32 v48, v48
	v_sub_f32_e32 v49, v49, v174
	v_exp_f32_e32 v49, v49
	v_sub_f32_e32 v50, v50, v174
	v_exp_f32_e32 v50, v50
	v_add_f32_e32 v213, v49, v48
	v_sub_f32_e32 v51, v51, v174
	v_exp_f32_e32 v51, v51
	v_add_f32_e32 v213, v50, v213
	v_cvt_pk_bf16_f32 v80, v48, v49
	v_sub_f32_e32 v52, v52, v174
	v_exp_f32_e32 v52, v52
	v_add_f32_e32 v213, v51, v213
	v_sub_f32_e32 v53, v53, v174
	v_exp_f32_e32 v53, v53
	v_add_f32_e32 v213, v52, v213
	v_cvt_pk_bf16_f32 v81, v50, v51
	v_sub_f32_e32 v54, v54, v174
	v_exp_f32_e32 v54, v54
	v_add_f32_e32 v213, v53, v213
	v_sub_f32_e32 v55, v55, v174
	v_exp_f32_e32 v55, v55
	v_add_f32_e32 v213, v54, v213
	v_cvt_pk_bf16_f32 v82, v52, v53
	v_sub_f32_e32 v56, v56, v174
	v_exp_f32_e32 v56, v56
	v_add_f32_e32 v213, v55, v213
	v_sub_f32_e32 v57, v57, v174
	v_exp_f32_e32 v57, v57
	v_add_f32_e32 v213, v56, v213
	v_cvt_pk_bf16_f32 v83, v54, v55
	v_sub_f32_e32 v58, v58, v174
	v_exp_f32_e32 v58, v58
	v_add_f32_e32 v213, v57, v213
	s_waitcnt lgkmcnt(3)
	v_mfma_f32_32x32x16_bf16 v[32:47], v[220:223], v[80:83], v[32:47]
	s_waitcnt lgkmcnt(2)
	v_mfma_f32_32x32x16_bf16 v[16:31], v[224:227], v[80:83], v[16:31]
	v_sub_f32_e32 v59, v59, v174
	v_exp_f32_e32 v59, v59
	v_add_f32_e32 v213, v58, v213
	v_cvt_pk_bf16_f32 v84, v56, v57
	v_sub_f32_e32 v60, v60, v174
	v_exp_f32_e32 v60, v60
	v_add_f32_e32 v213, v59, v213
	v_sub_f32_e32 v61, v61, v174
	v_exp_f32_e32 v61, v61
	v_add_f32_e32 v213, v60, v213
	v_cvt_pk_bf16_f32 v85, v58, v59
	v_sub_f32_e32 v62, v62, v174
	v_exp_f32_e32 v62, v62
	v_add_f32_e32 v213, v61, v213
	v_sub_f32_e32 v63, v63, v174
	v_exp_f32_e32 v63, v63
	v_add_f32_e32 v213, v62, v213
	v_cvt_pk_bf16_f32 v86, v60, v61
	v_add_f32_e32 v213, v63, v213
	v_cvt_pk_bf16_f32 v87, v62, v63
	v_add_f32_e32 v169, v169, v213
	s_nop 0
	s_waitcnt lgkmcnt(1)
	v_mfma_f32_32x32x16_bf16 v[32:47], v[228:231], v[84:87], v[32:47]
	s_waitcnt lgkmcnt(0)
	v_mfma_f32_32x32x16_bf16 v[16:31], v[232:235], v[84:87], v[16:31]
	s_branch .LBB0_296

.LBB0_301:
	s_add_i32 s13, s12, 1
	s_min_i32 s4, s13, s10
	s_lshl_b32 s4, s4, 6
	s_ashr_i32 s5, s4, 31
	s_lshl_b64 s[6:7], s[4:5], 7
	s_lshl_b64 s[4:5], s[4:5], 1
	v_lshl_add_u64 v[14:15], v[190:191], 0, s[6:7]
	v_lshl_add_u64 v[10:11], v[164:165], 0, s[4:5]
	global_load_dwordx4 v[6:9], v[14:15], off offset:-2048
	s_nop 0
	global_load_dwordx4 v[2:5], v[14:15], off offset:2048
	v_lshl_add_u64 v[14:15], v[166:167], 0, s[4:5]
	global_load_dwordx4 v[10:13], v[10:11], off
	s_nop 0
	global_load_dwordx4 v[112:115], v[14:15], off
	s_sub_i32 s4, s12, s11
	s_lshl_b32 s6, s12, 6
	s_and_b32 s14, s4, 1
	s_or_b32 s4, s6, 63
	s_cmp_le_i32 s4, s8
	s_cselect_b64 s[4:5], -1, 0
	s_cmp_gt_i32 s6, s9
	s_mul_i32 s7, s14, 0x4800
	s_cselect_b64 s[16:17], -1, 0
	s_and_b64 s[16:17], s[4:5], s[16:17]
	v_or_b32_e32 v14, s7, v129
	s_and_b64 vcc, exec, s[16:17]
	s_cbranch_vccnz .LBB0_307
	s_cmp_le_i32 s6, s9
	s_cbranch_scc1 .Lnsw1_elo
	s_add_i32 s4, s6, 1
	s_cmp_gt_i32 s4, s8
	s_cbranch_scc1 .Lnsw1_ehe
	v_and_b32_e32 v173, 31, v133
	v_bfe_u32 v213, v133, 5, 1
	v_lshlrev_b32_e32 v213, 3, v213
	v_sub_u32_e32 v173, v173, v213
	s_sub_i32 s4, s8, s6
	v_add_u32_e32 v173, s4, v173
	v_add_u32_e32 v213, 0xffffffe0, v173
	v_mov_b32_e32 v174, 0xff800000
	v_mad_u32_u24 v0, v218, s37, v14
	v_lshl_add_u32 v215, v159, 1, v14
	ds_read_b128 v[220:223], v0
	ds_read_b128 v[236:239], v0 offset:4608
	ds_read_b128 v[224:227], v0 offset:32
	ds_read_b128 v[240:243], v0 offset:4640
	ds_read_b128 v[228:231], v0 offset:64
	ds_read_b128 v[244:247], v0 offset:4672
	ds_read_b128 v[232:235], v0 offset:96
	ds_read_b128 v[248:251], v0 offset:4704
	ds_read_b128 v[64:67], v215 offset:9216
	ds_read_b128 v[68:71], v215 offset:13824
	ds_read_b128 v[72:75], v215 offset:9248
	ds_read_b128 v[76:79], v215 offset:13856
	s_waitcnt lgkmcnt(11)
	v_mfma_f32_32x32x16_bf16 v[80:95], v[220:223], v[96:99], 0
	s_waitcnt lgkmcnt(10)
	v_mfma_f32_32x32x16_bf16 v[48:63], v[236:239], v[96:99], 0
	s_waitcnt lgkmcnt(9)
	v_mfma_f32_32x32x16_bf16 v[80:95], v[224:227], v[100:103], v[80:95]
	s_waitcnt lgkmcnt(8)
	v_mfma_f32_32x32x16_bf16 v[48:63], v[240:243], v[100:103], v[48:63]
	s_waitcnt lgkmcnt(7)
	v_mfma_f32_32x32x16_bf16 v[80:95], v[228:231], v[104:107], v[80:95]
	s_waitcnt lgkmcnt(6)
	v_mfma_f32_32x32x16_bf16 v[48:63], v[244:247], v[104:107], v[48:63]
	s_waitcnt lgkmcnt(5)
	v_mfma_f32_32x32x16_bf16 v[80:95], v[232:235], v[108:111], v[80:95]
	s_waitcnt lgkmcnt(4)
	v_mfma_f32_32x32x16_bf16 v[48:63], v[248:251], v[108:111], v[48:63]
	ds_read_b128 v[220:223], v215 offset:9280
	ds_read_b128 v[224:227], v215 offset:13888
	ds_read_b128 v[228:231], v215 offset:9312
	ds_read_b128 v[232:235], v215 offset:13920
	s_nop 7
	s_nop 3
	v_cmp_le_i32_e64 vcc, 0, v213
	v_cmp_le_i32_e64 s[4:5], 1, v213
	v_cmp_le_i32_e64 s[6:7], 2, v213
	v_cndmask_b32_e32 v48, v174, v48, vcc
	v_cmp_le_i32_e64 vcc, 3, v213
	v_cndmask_b32_e64 v49, v174, v49, s[4:5]
	v_cmp_le_i32_e64 s[4:5], 4, v213
	v_cndmask_b32_e64 v50, v174, v50, s[6:7]
	v_cmp_le_i32_e64 s[6:7], 5, v213
	v_cndmask_b32_e32 v51, v174, v51, vcc
	v_cmp_le_i32_e64 vcc, 6, v213
	v_cndmask_b32_e64 v52, v174, v52, s[4:5]
	v_cmp_le_i32_e64 s[4:5], 7, v213
	v_cndmask_b32_e64 v53, v174, v53, s[6:7]
	v_cmp_le_i32_e64 s[6:7], 16, v213
	v_cndmask_b32_e32 v54, v174, v54, vcc
	v_cmp_le_i32_e64 vcc, 17, v213
	v_cndmask_b32_e64 v55, v174, v55, s[4:5]
	v_cmp_le_i32_e64 s[4:5], 18, v213
	v_cndmask_b32_e64 v56, v174, v56, s[6:7]
	v_cmp_le_i32_e64 s[6:7], 19, v213
	v_cndmask_b32_e32 v57, v174, v57, vcc
	v_cmp_le_i32_e64 vcc, 20, v213
	v_cndmask_b32_e64 v58, v174, v58, s[4:5]
	v_cmp_le_i32_e64 s[4:5], 21, v213
	v_cndmask_b32_e64 v59, v174, v59, s[6:7]
	v_cmp_le_i32_e64 s[6:7], 22, v213
	v_cndmask_b32_e32 v60, v174, v60, vcc
	v_cmp_le_i32_e64 vcc, 23, v213
	v_cndmask_b32_e64 v61, v174, v61, s[4:5]
	s_nop 0
	v_cndmask_b32_e64 v62, v174, v62, s[6:7]
	s_nop 0
	v_cndmask_b32_e32 v63, v174, v63, vcc
	s_nop 0
	v_max3_f32 v0, v80, v81, v82
	v_max3_f32 v216, v88, v89, v90
	v_max3_f32 v0, v0, v83, v84
	v_max3_f32 v216, v216, v91, v92
	v_max3_f32 v0, v0, v85, v86
	v_max3_f32 v216, v216, v93, v94
	v_max3_f32 v0, v0, v87, v95
	v_max_f32_e32 v0, v0, v216
	v_max3_f32 v175, v48, v49, v50
	v_max3_f32 v214, v56, v57, v58
	v_max3_f32 v175, v175, v51, v52
	v_max3_f32 v214, v214, v59, v60
	v_max3_f32 v175, v175, v53, v54
	v_max3_f32 v214, v214, v61, v62
	v_max3_f32 v175, v175, v55, v63
	v_max_f32_e32 v175, v175, v214
	v_cmp_gt_f32_e32 vcc, v0, v219
	s_cmp_eq_u64 vcc, 0
	s_cbranch_scc1 .Lnsw1eho_keep0
	s_nop 0
	ds_bpermute_b32 v216, v119, v0
	s_waitcnt lgkmcnt(0)
	v_max_f32_e32 v0, v0, v216
	v_max_f32_e32 v173, v168, v0
	v_sub_f32_e32 v0, v168, v173
	v_exp_f32_e32 v0, v0
	v_mov_b32_e32 v168, v173
	v_add_f32_e32 v219, 0x41200000, v173
	v_mul_f32_e32 v169, v169, v0
	v_pk_mul_f32 v[46:47], v[46:47], v[0:1] op_sel_hi:[1,0]
	v_pk_mul_f32 v[44:45], v[44:45], v[0:1] op_sel_hi:[1,0]
	v_pk_mul_f32 v[42:43], v[42:43], v[0:1] op_sel_hi:[1,0]
	v_pk_mul_f32 v[40:41], v[40:41], v[0:1] op_sel_hi:[1,0]
	v_pk_mul_f32 v[38:39], v[38:39], v[0:1] op_sel_hi:[1,0]
	v_pk_mul_f32 v[36:37], v[36:37], v[0:1] op_sel_hi:[1,0]
	v_pk_mul_f32 v[34:35], v[34:35], v[0:1] op_sel_hi:[1,0]
	v_pk_mul_f32 v[32:33], v[32:33], v[0:1] op_sel_hi:[1,0]
	v_pk_mul_f32 v[30:31], v[30:31], v[0:1] op_sel_hi:[1,0]
	v_pk_mul_f32 v[28:29], v[28:29], v[0:1] op_sel_hi:[1,0]
	v_pk_mul_f32 v[26:27], v[26:27], v[0:1] op_sel_hi:[1,0]
	v_pk_mul_f32 v[24:25], v[24:25], v[0:1] op_sel_hi:[1,0]
	v_pk_mul_f32 v[22:23], v[22:23], v[0:1] op_sel_hi:[1,0]
	v_pk_mul_f32 v[20:21], v[20:21], v[0:1] op_sel_hi:[1,0]
	v_pk_mul_f32 v[18:19], v[18:19], v[0:1] op_sel_hi:[1,0]
	v_pk_mul_f32 v[16:17], v[16:17], v[0:1] op_sel_hi:[1,0]

.LBB0_334:
	v_lshlrev_b32_e32 v9, 16, v9
	v_mul_f32_e32 v9, 0x3fb8aa3b, v9
	v_lshlrev_b32_e32 v8, 16, v62
	v_lshlrev_b32_e32 v62, 16, v88
	v_lshlrev_b32_e32 v63, 16, v67
	v_exp_f32_e32 v9, v9
	v_lshlrev_b32_e32 v20, 16, v20
	v_sub_f32_e32 v63, v63, v62
	v_add_f32_e32 v67, -1.0, v20
	v_fma_f32 v63, v16, v63, v62
	v_fma_f32 v67, v19, v67, 1.0
	v_lshlrev_b32_e32 v65, 16, v68
	v_lshlrev_b32_e32 v66, 16, v66
	v_mul_f32_e32 v67, v67, v63
	v_sub_f32_e32 v66, v66, v65
	ds_write2st64_b32 v32, v9, v67 offset0:16 offset1:32
	v_mul_f32_e64 v9, v18, -v63
	v_fma_f32 v66, v17, v66, v65
	v_mul_f32_e32 v9, v21, v9
	v_lshlrev_b32_e32 v22, 16, v22
	v_lshlrev_b32_e32 v0, 16, v89
	ds_write2st64_b32 v32, v66, v9 offset0:48 offset1:64
	v_mul_f32_e64 v9, -v9, v20
	v_mul_f32_e32 v22, 0x3fb8aa3b, v22
	v_sub_f32_e32 v8, v8, v0
	ds_write_b32 v32, v9 offset:20480
	v_lshlrev_b32_e32 v9, 16, v61
	v_lshlrev_b32_e32 v20, 16, v57
	v_exp_f32_e32 v22, v22
	v_lshlrev_b32_e32 v23, 16, v23
	v_fma_f32 v8, v3, v8, v0
	v_lshlrev_b32_e32 v21, 16, v58
	v_sub_f32_e32 v0, v0, v9
	v_sub_f32_e32 v57, v62, v20
	v_add_f32_e32 v61, -1.0, v23
	v_fma_f32 v0, v3, v0, v9
	v_fma_f32 v57, v16, v57, v20
	v_sub_f32_e32 v58, v65, v21
	v_fma_f32 v61, v19, v61, 1.0
	v_fma_f32 v58, v17, v58, v21
	v_mul_f32_e32 v61, v61, v57
	ds_write2st64_b32 v32, v8, v0 offset1:1
	ds_write_b32 v33, v22 offset:256
	ds_write_b32 v34, v61 offset:256
	ds_write_b32 v35, v58 offset:256
	v_mul_f32_e64 v0, v18, -v57
	v_mul_f32_e32 v0, v24, v0
	ds_write_b32 v36, v0 offset:256
	v_mul_f32_e64 v0, -v0, v23
	v_lshlrev_b32_e32 v23, 16, v25
	v_mul_f32_e32 v23, 0x3fb8aa3b, v23
	ds_write_b32 v37, v0 offset:256
	v_lshlrev_b32_e32 v0, 16, v64
	v_lshlrev_b32_e32 v8, 16, v60
	v_exp_f32_e32 v23, v23
	v_lshlrev_b32_e32 v24, 16, v27
	v_lshlrev_b32_e32 v22, 16, v56
	v_sub_f32_e32 v9, v9, v0
	v_sub_f32_e32 v20, v20, v8
	v_add_f32_e32 v25, -1.0, v24
	v_fma_f32 v9, v3, v9, v0
	v_fma_f32 v20, v16, v20, v8
	v_sub_f32_e32 v21, v21, v22
	v_fma_f32 v25, v19, v25, 1.0
	v_fma_f32 v21, v17, v21, v22
	v_mul_f32_e32 v25, v25, v20
	ds_write_b32 v32, v9 offset:512
	ds_write_b32 v33, v23 offset:512
	ds_write_b32 v34, v25 offset:512
	ds_write_b32 v35, v21 offset:512
	v_mul_f32_e64 v9, v18, -v20
	v_mul_f32_e32 v9, v26, v9
	ds_write_b32 v36, v9 offset:512
	v_mul_f32_e64 v9, -v9, v24
	ds_write_b32 v37, v9 offset:512
	v_lshlrev_b32_e32 v9, 16, v55
	v_lshlrev_b32_e32 v20, 16, v59
	v_sub_f32_e32 v0, v0, v9
	v_lshlrev_b32_e32 v21, 16, v54
	v_fmac_f32_e32 v9, v3, v0
	v_sub_f32_e32 v0, v8, v20
	v_fmac_f32_e32 v20, v16, v0
	v_sub_f32_e32 v0, v22, v21
	v_fmac_f32_e32 v21, v17, v0
	v_lshlrev_b32_e32 v0, 16, v28
	v_mul_f32_e32 v0, 0x3fb8aa3b, v0
	v_exp_f32_e32 v0, v0
	v_lshlrev_b32_e32 v8, 16, v29
	v_add_f32_e32 v22, -1.0, v8
	v_fma_f32 v22, v19, v22, 1.0
	v_mul_f32_e32 v22, v22, v20
	ds_write_b32 v32, v9 offset:768
	ds_write_b32 v33, v0 offset:768
	ds_write_b32 v34, v22 offset:768
	ds_write_b32 v35, v21 offset:768
	v_mul_f32_e64 v0, v18, -v20
	v_mul_f32_e32 v0, v30, v0
	s_min_u32 s5, s4, 0xfd
	ds_write_b32 v36, v0 offset:768
	v_mul_f32_e64 v0, -v0, v8
	v_lshl_add_u32 v8, s5, 4, v38
	ds_write_b32 v37, v0 offset:768
	v_max_i32_e32 v0, 1, v8
	v_add_u32_e32 v0, -1, v0
	v_lshl_add_u64 v[20:21], s[56:57], 0, v[0:1]
	v_mad_u64_u32 v[22:23], s[6:7], v20, s29, v[4:5]
	v_mad_i32_i24 v23, v21, s29, v23
	s_waitcnt lgkmcnt(0)
	s_barrier
	ds_read_b128 v[220:223], v40 offset:16384
	ds_read_b128 v[236:239], v40 offset:8192
	ds_read2st64_b32 v[108:109], v39 offset0:0 offset1:1
	ds_read_b128 v[244:247], v40 offset:20480
	ds_read_b128 v[228:231], v40 offset:4096
	ds_read_b128 v[100:103], v40 offset:0
	ds_read_b128 v[224:227], v40 offset:16640
	ds_read_b128 v[240:243], v40 offset:8448
	ds_read2st64_b32 v[110:111], v39 offset0:2 offset1:3
	ds_read_b128 v[248:251], v40 offset:20736
	ds_read_b128 v[232:235], v40 offset:4352
	s_mov_b64 s[6:7], 0xd00
	global_load_ushort v55, v[22:23], off
	global_load_ushort v57, v[22:23], off offset:1024
	global_load_ushort v54, v[22:23], off offset:2048
	v_lshl_add_u64 v[112:113], v[22:23], 0, s[6:7]
	global_load_ushort v59, v[112:113], off
	global_load_ushort v60, v[112:113], off offset:1024
	global_load_ushort v56, v[112:113], off offset:2048
	v_lshl_add_u64 v[114:115], v[112:113], 0, s[6:7]
	global_load_ushort v61, v[114:115], off
	global_load_ushort v62, v[114:115], off offset:1024
	global_load_ushort v58, v[114:115], off offset:2048
	v_lshl_add_u64 v[116:117], v[114:115], 0, s[6:7]
	global_load_ushort v64, v[116:117], off
	global_load_ushort v67, v[116:117], off offset:1024
	global_load_ushort v63, v[116:117], off offset:2048
	v_lshl_add_u64 v[118:119], v[116:117], 0, s[6:7]
	v_ashrrev_i32_e32 v9, 31, v8
	v_lshl_add_u64 v[120:121], s[56:57], 0, v[8:9]
	v_lshlrev_b32_e32 v83, 1, v2
	v_lshlrev_b64 v[122:123], 10, v[120:121]
	v_or_b32_e32 v122, v122, v83
	v_lshl_add_u64 v[124:125], s[0:1], 0, v[122:123]
	v_lshl_add_u64 v[126:127], s[24:25], 0, v[122:123]
	v_lshlrev_b64 v[128:129], 5, v[120:121]
	v_lshl_add_u64 v[128:129], s[58:59], 0, v[128:129]
	global_load_ushort v66, v[118:119], off
	global_load_ushort v68, v[118:119], off offset:1024
	global_load_ushort v65, v[118:119], off offset:2048
	global_load_ushort v9, v[124:125], off
	global_load_dword v24, v[128:129], off offset:32
	global_load_ushort v20, v[126:127], off
	global_load_dword v21, v[128:129], off
	global_load_ushort v22, v[124:125], off offset:1024
	global_load_ushort v23, v[126:127], off offset:1024
	global_load_ushort v25, v[124:125], off offset:2048
	global_load_ushort v27, v[126:127], off offset:2048
	global_load_dword v30, v[128:129], off offset:96
	global_load_dword v26, v[128:129], off offset:64
	global_load_ushort v28, v[124:125], off offset:3072
	global_load_ushort v29, v[126:127], off offset:3072
	v_mov_b32_e32 v0, v31
	v_mov_b32_e32 v84, v40
	v_mov_b32_e32 v86, 0
	v_mov_b32_e32 v85, v39
	s_mov_b32 s5, 0
	s_waitcnt lgkmcnt(6)
	v_pk_mul_f32 v[88:89], v[12:13], v[220:221]
	v_pk_fma_f32 v[88:89], v[10:11], v[222:223], v[88:89]
	v_add_f32_e32 v90, v88, v89
	v_pk_mul_f32 v[92:93], v[108:109], v[236:237] op_sel_hi:[0,1]
	v_pk_mul_f32 v[94:95], v[108:109], v[238:239] op_sel_hi:[0,1]
	v_add_f32_dpp v90, v90, v90 row_ror:8 row_mask:0xf bank_mask:0xf bound_ctrl:1
	ds_read_b128 v[220:223], v40 offset:16896
	ds_read_b128 v[236:239], v40 offset:8704
	v_add_f32_dpp v90, v90, v90 row_ror:4 row_mask:0xf bank_mask:0xf bound_ctrl:1
	s_nop 1
	v_add_f32_dpp v90, v90, v90 row_ror:2 row_mask:0xf bank_mask:0xf bound_ctrl:1
	ds_read_b128 v[104:107], v40 offset:256
	s_nop 0
	v_add_f32_dpp v90, v90, v90 row_ror:1 row_mask:0xf bank_mask:0xf bound_ctrl:1
	v_pk_fma_f32 v[92:93], v[90:91], v[244:245], v[92:93] op_sel_hi:[0,1,1]
	v_pk_fma_f32 v[94:95], v[90:91], v[246:247], v[94:95] op_sel_hi:[0,1,1]
	ds_read_b128 v[244:247], v40 offset:20992
	v_pk_fma_f32 v[12:13], v[12:13], v[228:229], v[92:93]
	v_pk_fma_f32 v[10:11], v[10:11], v[230:231], v[94:95]
	ds_read_b128 v[228:231], v40 offset:4608
	s_waitcnt lgkmcnt(5)
	v_pk_mul_f32 v[88:89], v[12:13], v[224:225]
	v_pk_fma_f32 v[88:89], v[10:11], v[226:227], v[88:89]
	v_add_f32_e32 v90, v88, v89
	v_pk_mul_f32 v[92:93], v[108:109], v[240:241] op_sel:[1,0] op_sel_hi:[1,1]
	v_pk_mul_f32 v[94:95], v[108:109], v[242:243] op_sel:[1,0] op_sel_hi:[1,1]
	v_add_f32_dpp v90, v90, v90 row_ror:8 row_mask:0xf bank_mask:0xf bound_ctrl:1
	ds_read_b128 v[224:227], v40 offset:17152
	ds_read_b128 v[240:243], v40 offset:8960
	v_add_f32_dpp v90, v90, v90 row_ror:4 row_mask:0xf bank_mask:0xf bound_ctrl:1
	v_pk_mul_f32 v[100:101], v[12:13], v[100:101]
	v_pk_fma_f32 v[100:101], v[10:11], v[102:103], v[100:101]
	v_add_f32_dpp v90, v90, v90 row_ror:2 row_mask:0xf bank_mask:0xf bound_ctrl:1
	v_add_f32_e32 v96, v100, v101
	ds_read_b128 v[100:103], v40 offset:512
	v_add_f32_dpp v90, v90, v90 row_ror:1 row_mask:0xf bank_mask:0xf bound_ctrl:1
	ds_read2st64_b32 v[108:109], v39 offset0:4 offset1:5
	v_pk_fma_f32 v[92:93], v[90:91], v[248:249], v[92:93] op_sel_hi:[0,1,1]
	v_pk_fma_f32 v[94:95], v[90:91], v[250:251], v[94:95] op_sel_hi:[0,1,1]
	ds_read_b128 v[248:251], v40 offset:21248
	v_pk_fma_f32 v[12:13], v[12:13], v[232:233], v[92:93]
	v_pk_fma_f32 v[10:11], v[10:11], v[234:235], v[94:95]
	ds_read_b128 v[232:235], v40 offset:4864
	s_waitcnt lgkmcnt(6)
	v_pk_mul_f32 v[88:89], v[12:13], v[220:221]
	v_pk_fma_f32 v[88:89], v[10:11], v[222:223], v[88:89]
	v_add_f32_e32 v90, v88, v89
	v_pk_mul_f32 v[92:93], v[110:111], v[236:237] op_sel_hi:[0,1]
	v_pk_mul_f32 v[94:95], v[110:111], v[238:239] op_sel_hi:[0,1]
	v_add_f32_dpp v90, v90, v90 row_ror:8 row_mask:0xf bank_mask:0xf bound_ctrl:1
	ds_read_b128 v[220:223], v40 offset:17408
	ds_read_b128 v[236:239], v40 offset:9216
	v_add_f32_dpp v90, v90, v90 row_ror:4 row_mask:0xf bank_mask:0xf bound_ctrl:1
	v_pk_mul_f32 v[104:105], v[12:13], v[104:105]
	v_pk_fma_f32 v[104:105], v[10:11], v[106:107], v[104:105]
	v_add_f32_dpp v90, v90, v90 row_ror:2 row_mask:0xf bank_mask:0xf bound_ctrl:1
	v_add_f32_e32 v97, v104, v105
	ds_read_b128 v[104:107], v40 offset:768
	v_add_f32_dpp v90, v90, v90 row_ror:1 row_mask:0xf bank_mask:0xf bound_ctrl:1
	v_pk_fma_f32 v[92:93], v[90:91], v[244:245], v[92:93] op_sel_hi:[0,1,1]
	v_pk_fma_f32 v[94:95], v[90:91], v[246:247], v[94:95] op_sel_hi:[0,1,1]
	ds_read_b128 v[244:247], v40 offset:21504
	v_pk_fma_f32 v[12:13], v[12:13], v[228:229], v[92:93]
	v_pk_fma_f32 v[10:11], v[10:11], v[230:231], v[94:95]
	ds_read_b128 v[228:231], v40 offset:5120
	s_waitcnt lgkmcnt(5)
	v_pk_mul_f32 v[88:89], v[12:13], v[224:225]
	v_pk_fma_f32 v[88:89], v[10:11], v[226:227], v[88:89]
	v_add_f32_e32 v90, v88, v89
	v_pk_mul_f32 v[92:93], v[110:111], v[240:241] op_sel:[1,0] op_sel_hi:[1,1]
	v_pk_mul_f32 v[94:95], v[110:111], v[242:243] op_sel:[1,0] op_sel_hi:[1,1]
	v_add_f32_dpp v90, v90, v90 row_ror:8 row_mask:0xf bank_mask:0xf bound_ctrl:1
	ds_read_b128 v[224:227], v40 offset:17664
	ds_read_b128 v[240:243], v40 offset:9472
	v_add_f32_dpp v90, v90, v90 row_ror:4 row_mask:0xf bank_mask:0xf bound_ctrl:1
	v_pk_mul_f32 v[100:101], v[12:13], v[100:101]
	v_pk_fma_f32 v[100:101], v[10:11], v[102:103], v[100:101]
	v_add_f32_dpp v90, v90, v90 row_ror:2 row_mask:0xf bank_mask:0xf bound_ctrl:1
	v_add_f32_e32 v98, v100, v101
	ds_read_b128 v[100:103], v40 offset:1024
	v_add_f32_dpp v90, v90, v90 row_ror:1 row_mask:0xf bank_mask:0xf bound_ctrl:1
	ds_read2st64_b32 v[110:111], v39 offset0:6 offset1:7
	v_pk_fma_f32 v[92:93], v[90:91], v[248:249], v[92:93] op_sel_hi:[0,1,1]
	v_pk_fma_f32 v[94:95], v[90:91], v[250:251], v[94:95] op_sel_hi:[0,1,1]
	ds_read_b128 v[248:251], v40 offset:21760
	v_pk_fma_f32 v[12:13], v[12:13], v[232:233], v[92:93]
	v_pk_fma_f32 v[10:11], v[10:11], v[234:235], v[94:95]
	ds_read_b128 v[232:235], v40 offset:5376
	s_waitcnt lgkmcnt(6)
	v_pk_mul_f32 v[88:89], v[12:13], v[220:221]
	v_pk_fma_f32 v[88:89], v[10:11], v[222:223], v[88:89]
	v_add_f32_e32 v90, v88, v89
	v_pk_mul_f32 v[92:93], v[108:109], v[236:237] op_sel_hi:[0,1]
	v_pk_mul_f32 v[94:95], v[108:109], v[238:239] op_sel_hi:[0,1]
	v_add_f32_dpp v90, v90, v90 row_ror:8 row_mask:0xf bank_mask:0xf bound_ctrl:1
	ds_read_b128 v[220:223], v40 offset:17920
	ds_read_b128 v[236:239], v40 offset:9728
	v_add_f32_dpp v90, v90, v90 row_ror:4 row_mask:0xf bank_mask:0xf bound_ctrl:1
	v_pk_mul_f32 v[104:105], v[12:13], v[104:105]
	v_pk_fma_f32 v[104:105], v[10:11], v[106:107], v[104:105]
	v_add_f32_dpp v90, v90, v90 row_ror:2 row_mask:0xf bank_mask:0xf bound_ctrl:1
	v_add_f32_e32 v99, v104, v105
	ds_read_b128 v[104:107], v40 offset:1280
	v_add_f32_dpp v90, v90, v90 row_ror:1 row_mask:0xf bank_mask:0xf bound_ctrl:1
	v_pk_fma_f32 v[92:93], v[90:91], v[244:245], v[92:93] op_sel_hi:[0,1,1]
	v_pk_fma_f32 v[94:95], v[90:91], v[246:247], v[94:95] op_sel_hi:[0,1,1]
	ds_read_b128 v[244:247], v40 offset:22016
	v_pk_fma_f32 v[12:13], v[12:13], v[228:229], v[92:93]
	v_pk_fma_f32 v[10:11], v[10:11], v[230:231], v[94:95]
	ds_read_b128 v[228:231], v40 offset:5632
	s_waitcnt lgkmcnt(5)
	v_pk_mul_f32 v[88:89], v[12:13], v[224:225]
	v_pk_fma_f32 v[88:89], v[10:11], v[226:227], v[88:89]
	v_add_f32_e32 v90, v88, v89
	v_pk_mul_f32 v[92:93], v[108:109], v[240:241] op_sel:[1,0] op_sel_hi:[1,1]
	v_pk_mul_f32 v[94:95], v[108:109], v[242:243] op_sel:[1,0] op_sel_hi:[1,1]
	v_add_f32_dpp v90, v90, v90 row_ror:8 row_mask:0xf bank_mask:0xf bound_ctrl:1
	ds_read_b128 v[224:227], v40 offset:18176
	ds_read_b128 v[240:243], v40 offset:9984
	v_add_f32_dpp v90, v90, v90 row_ror:4 row_mask:0xf bank_mask:0xf bound_ctrl:1
	v_pk_mul_f32 v[100:101], v[12:13], v[100:101]
	v_pk_fma_f32 v[100:101], v[10:11], v[102:103], v[100:101]
	v_add_f32_dpp v90, v90, v90 row_ror:2 row_mask:0xf bank_mask:0xf bound_ctrl:1
	v_add_f32_e32 v87, v100, v101
	ds_read_b128 v[100:103], v40 offset:1536
	v_add_f32_dpp v90, v90, v90 row_ror:1 row_mask:0xf bank_mask:0xf bound_ctrl:1
	ds_read2st64_b32 v[108:109], v39 offset0:8 offset1:9
	v_pk_fma_f32 v[92:93], v[90:91], v[248:249], v[92:93] op_sel_hi:[0,1,1]
	v_pk_fma_f32 v[94:95], v[90:91], v[250:251], v[94:95] op_sel_hi:[0,1,1]
	ds_read_b128 v[248:251], v40 offset:22272
	v_pk_fma_f32 v[12:13], v[12:13], v[232:233], v[92:93]
	v_pk_fma_f32 v[10:11], v[10:11], v[234:235], v[94:95]
	ds_read_b128 v[232:235], v40 offset:5888
	s_waitcnt lgkmcnt(6)
	v_pk_mul_f32 v[88:89], v[12:13], v[220:221]
	v_pk_fma_f32 v[88:89], v[10:11], v[222:223], v[88:89]
	v_add_f32_e32 v90, v88, v89
	v_pk_mul_f32 v[92:93], v[110:111], v[236:237] op_sel_hi:[0,1]
	v_pk_mul_f32 v[94:95], v[110:111], v[238:239] op_sel_hi:[0,1]
	v_add_f32_dpp v90, v90, v90 row_ror:8 row_mask:0xf bank_mask:0xf bound_ctrl:1
	ds_read_b128 v[220:223], v40 offset:18432
	ds_read_b128 v[236:239], v40 offset:10240
	v_add_f32_dpp v90, v90, v90 row_ror:4 row_mask:0xf bank_mask:0xf bound_ctrl:1
	v_pk_mul_f32 v[104:105], v[12:13], v[104:105]
	v_pk_fma_f32 v[104:105], v[10:11], v[106:107], v[104:105]
	v_add_f32_dpp v90, v90, v90 row_ror:2 row_mask:0xf bank_mask:0xf bound_ctrl:1
	v_add_f32_e32 v217, v104, v105
	ds_read_b128 v[104:107], v40 offset:1792
	v_add_f32_dpp v90, v90, v90 row_ror:1 row_mask:0xf bank_mask:0xf bound_ctrl:1
	v_pk_fma_f32 v[92:93], v[90:91], v[244:245], v[92:93] op_sel_hi:[0,1,1]
	v_pk_fma_f32 v[94:95], v[90:91], v[246:247], v[94:95] op_sel_hi:[0,1,1]
	ds_read_b128 v[244:247], v40 offset:22528
	v_pk_fma_f32 v[12:13], v[12:13], v[228:229], v[92:93]
	v_pk_fma_f32 v[10:11], v[10:11], v[230:231], v[94:95]
	ds_read_b128 v[228:231], v40 offset:6144
	s_waitcnt lgkmcnt(5)
	v_pk_mul_f32 v[88:89], v[12:13], v[224:225]
	v_pk_fma_f32 v[88:89], v[10:11], v[226:227], v[88:89]
	v_add_f32_e32 v90, v88, v89
	v_pk_mul_f32 v[92:93], v[110:111], v[240:241] op_sel:[1,0] op_sel_hi:[1,1]
	v_pk_mul_f32 v[94:95], v[110:111], v[242:243] op_sel:[1,0] op_sel_hi:[1,1]
	v_add_f32_dpp v90, v90, v90 row_ror:8 row_mask:0xf bank_mask:0xf bound_ctrl:1
	ds_read_b128 v[224:227], v40 offset:18688
	ds_read_b128 v[240:243], v40 offset:10496
	v_add_f32_dpp v90, v90, v90 row_ror:4 row_mask:0xf bank_mask:0xf bound_ctrl:1
	v_pk_mul_f32 v[100:101], v[12:13], v[100:101]
	v_pk_fma_f32 v[100:101], v[10:11], v[102:103], v[100:101]
	v_add_f32_dpp v90, v90, v90 row_ror:2 row_mask:0xf bank_mask:0xf bound_ctrl:1
	v_add_f32_e32 v218, v100, v101
	ds_read_b128 v[100:103], v40 offset:2048
	v_add_f32_dpp v90, v90, v90 row_ror:1 row_mask:0xf bank_mask:0xf bound_ctrl:1
	ds_read2st64_b32 v[110:111], v39 offset0:10 offset1:11
	v_pk_fma_f32 v[92:93], v[90:91], v[248:249], v[92:93] op_sel_hi:[0,1,1]
	v_pk_fma_f32 v[94:95], v[90:91], v[250:251], v[94:95] op_sel_hi:[0,1,1]
	ds_read_b128 v[248:251], v40 offset:22784
	v_pk_fma_f32 v[12:13], v[12:13], v[232:233], v[92:93]
	v_pk_fma_f32 v[10:11], v[10:11], v[234:235], v[94:95]
	ds_read_b128 v[232:235], v40 offset:6400
	s_waitcnt lgkmcnt(6)
	v_pk_mul_f32 v[88:89], v[12:13], v[220:221]
	v_pk_fma_f32 v[88:89], v[10:11], v[222:223], v[88:89]
	v_add_f32_e32 v90, v88, v89
	v_pk_mul_f32 v[92:93], v[108:109], v[236:237] op_sel_hi:[0,1]
	v_pk_mul_f32 v[94:95], v[108:109], v[238:239] op_sel_hi:[0,1]
	v_add_f32_dpp v90, v90, v90 row_ror:8 row_mask:0xf bank_mask:0xf bound_ctrl:1
	ds_read_b128 v[220:223], v40 offset:18944
	ds_read_b128 v[236:239], v40 offset:10752
	v_add_f32_dpp v90, v90, v90 row_ror:4 row_mask:0xf bank_mask:0xf bound_ctrl:1
	v_pk_mul_f32 v[104:105], v[12:13], v[104:105]
	v_pk_fma_f32 v[104:105], v[10:11], v[106:107], v[104:105]
	v_add_f32_dpp v90, v90, v90 row_ror:2 row_mask:0xf bank_mask:0xf bound_ctrl:1
	v_add_f32_e32 v219, v104, v105
	ds_read_b128 v[104:107], v40 offset:2304
	v_add_f32_dpp v90, v90, v90 row_ror:1 row_mask:0xf bank_mask:0xf bound_ctrl:1
	v_pk_fma_f32 v[92:93], v[90:91], v[244:245], v[92:93] op_sel_hi:[0,1,1]
	v_pk_fma_f32 v[94:95], v[90:91], v[246:247], v[94:95] op_sel_hi:[0,1,1]
	ds_read_b128 v[244:247], v40 offset:23040
	v_pk_fma_f32 v[12:13], v[12:13], v[228:229], v[92:93]
	v_pk_fma_f32 v[10:11], v[10:11], v[230:231], v[94:95]
	ds_read_b128 v[228:231], v40 offset:6656
	s_waitcnt lgkmcnt(5)
	v_pk_mul_f32 v[88:89], v[12:13], v[224:225]
	v_pk_fma_f32 v[88:89], v[10:11], v[226:227], v[88:89]
	v_add_f32_e32 v90, v88, v89
	v_pk_mul_f32 v[92:93], v[108:109], v[240:241] op_sel:[1,0] op_sel_hi:[1,1]
	v_pk_mul_f32 v[94:95], v[108:109], v[242:243] op_sel:[1,0] op_sel_hi:[1,1]
	v_add_f32_dpp v90, v90, v90 row_ror:8 row_mask:0xf bank_mask:0xf bound_ctrl:1
	ds_read_b128 v[224:227], v40 offset:19200
	ds_read_b128 v[240:243], v40 offset:11008
	v_add_f32_dpp v90, v90, v90 row_ror:4 row_mask:0xf bank_mask:0xf bound_ctrl:1
	v_pk_mul_f32 v[100:101], v[12:13], v[100:101]
	v_pk_fma_f32 v[100:101], v[10:11], v[102:103], v[100:101]
	v_add_f32_dpp v90, v90, v90 row_ror:2 row_mask:0xf bank_mask:0xf bound_ctrl:1
	v_add_f32_e32 v187, v100, v101
	ds_read_b128 v[100:103], v40 offset:2560
	v_add_f32_dpp v90, v90, v90 row_ror:1 row_mask:0xf bank_mask:0xf bound_ctrl:1
	ds_read2st64_b32 v[108:109], v39 offset0:12 offset1:13
	v_pk_fma_f32 v[92:93], v[90:91], v[248:249], v[92:93] op_sel_hi:[0,1,1]
	v_pk_fma_f32 v[94:95], v[90:91], v[250:251], v[94:95] op_sel_hi:[0,1,1]
	ds_read_b128 v[248:251], v40 offset:23296
	v_pk_fma_f32 v[12:13], v[12:13], v[232:233], v[92:93]
	v_pk_fma_f32 v[10:11], v[10:11], v[234:235], v[94:95]
	ds_read_b128 v[232:235], v40 offset:6912
	s_waitcnt lgkmcnt(6)
	v_pk_mul_f32 v[88:89], v[12:13], v[220:221]
	v_pk_fma_f32 v[88:89], v[10:11], v[222:223], v[88:89]
	v_add_f32_e32 v90, v88, v89
	v_pk_mul_f32 v[92:93], v[110:111], v[236:237] op_sel_hi:[0,1]
	v_pk_mul_f32 v[94:95], v[110:111], v[238:239] op_sel_hi:[0,1]
	v_add_f32_dpp v90, v90, v90 row_ror:8 row_mask:0xf bank_mask:0xf bound_ctrl:1
	ds_read_b128 v[220:223], v40 offset:19456
	ds_read_b128 v[236:239], v40 offset:11264
	v_add_f32_dpp v90, v90, v90 row_ror:4 row_mask:0xf bank_mask:0xf bound_ctrl:1
	v_pk_mul_f32 v[104:105], v[12:13], v[104:105]
	v_pk_fma_f32 v[104:105], v[10:11], v[106:107], v[104:105]
	v_add_f32_dpp v90, v90, v90 row_ror:2 row_mask:0xf bank_mask:0xf bound_ctrl:1
	v_add_f32_e32 v190, v104, v105
	ds_read_b128 v[104:107], v40 offset:2816
	v_add_f32_dpp v90, v90, v90 row_ror:1 row_mask:0xf bank_mask:0xf bound_ctrl:1
	v_pk_fma_f32 v[92:93], v[90:91], v[244:245], v[92:93] op_sel_hi:[0,1,1]
	v_pk_fma_f32 v[94:95], v[90:91], v[246:247], v[94:95] op_sel_hi:[0,1,1]
	ds_read_b128 v[244:247], v40 offset:23552
	v_pk_fma_f32 v[12:13], v[12:13], v[228:229], v[92:93]
	v_pk_fma_f32 v[10:11], v[10:11], v[230:231], v[94:95]
	ds_read_b128 v[228:231], v40 offset:7168
	s_waitcnt lgkmcnt(5)
	v_pk_mul_f32 v[88:89], v[12:13], v[224:225]
	v_pk_fma_f32 v[88:89], v[10:11], v[226:227], v[88:89]
	v_add_f32_e32 v90, v88, v89
	v_pk_mul_f32 v[92:93], v[110:111], v[240:241] op_sel:[1,0] op_sel_hi:[1,1]
	v_pk_mul_f32 v[94:95], v[110:111], v[242:243] op_sel:[1,0] op_sel_hi:[1,1]
	v_add_f32_dpp v90, v90, v90 row_ror:8 row_mask:0xf bank_mask:0xf bound_ctrl:1
	ds_read_b128 v[224:227], v40 offset:19712
	ds_read_b128 v[240:243], v40 offset:11520
	v_add_f32_dpp v90, v90, v90 row_ror:4 row_mask:0xf bank_mask:0xf bound_ctrl:1
	v_pk_mul_f32 v[100:101], v[12:13], v[100:101]
	v_pk_fma_f32 v[100:101], v[10:11], v[102:103], v[100:101]
	v_add_f32_dpp v90, v90, v90 row_ror:2 row_mask:0xf bank_mask:0xf bound_ctrl:1
	v_add_f32_e32 v191, v100, v101
	ds_read_b128 v[100:103], v40 offset:3072
	v_add_f32_dpp v90, v90, v90 row_ror:1 row_mask:0xf bank_mask:0xf bound_ctrl:1
	ds_read2st64_b32 v[110:111], v39 offset0:14 offset1:15
	v_pk_fma_f32 v[92:93], v[90:91], v[248:249], v[92:93] op_sel_hi:[0,1,1]
	v_pk_fma_f32 v[94:95], v[90:91], v[250:251], v[94:95] op_sel_hi:[0,1,1]
	ds_read_b128 v[248:251], v40 offset:23808
	v_pk_fma_f32 v[12:13], v[12:13], v[232:233], v[92:93]
	v_pk_fma_f32 v[10:11], v[10:11], v[234:235], v[94:95]
	ds_read_b128 v[232:235], v40 offset:7424
	s_waitcnt lgkmcnt(6)
	v_pk_mul_f32 v[88:89], v[12:13], v[220:221]
	v_pk_fma_f32 v[88:89], v[10:11], v[222:223], v[88:89]
	v_add_f32_e32 v90, v88, v89
	v_pk_mul_f32 v[92:93], v[108:109], v[236:237] op_sel_hi:[0,1]
	v_pk_mul_f32 v[94:95], v[108:109], v[238:239] op_sel_hi:[0,1]
	v_add_f32_dpp v90, v90, v90 row_ror:8 row_mask:0xf bank_mask:0xf bound_ctrl:1
	ds_read_b128 v[220:223], v40 offset:19968
	ds_read_b128 v[236:239], v40 offset:11776
	v_add_f32_dpp v90, v90, v90 row_ror:4 row_mask:0xf bank_mask:0xf bound_ctrl:1
	v_pk_mul_f32 v[104:105], v[12:13], v[104:105]
	v_pk_fma_f32 v[104:105], v[10:11], v[106:107], v[104:105]
	v_add_f32_dpp v90, v90, v90 row_ror:2 row_mask:0xf bank_mask:0xf bound_ctrl:1
	v_add_f32_e32 v200, v104, v105
	ds_read_b128 v[104:107], v40 offset:3328
	v_add_f32_dpp v90, v90, v90 row_ror:1 row_mask:0xf bank_mask:0xf bound_ctrl:1
	v_pk_fma_f32 v[92:93], v[90:91], v[244:245], v[92:93] op_sel_hi:[0,1,1]
	v_pk_fma_f32 v[94:95], v[90:91], v[246:247], v[94:95] op_sel_hi:[0,1,1]
	ds_read_b128 v[244:247], v40 offset:24064
	v_pk_fma_f32 v[12:13], v[12:13], v[228:229], v[92:93]
	v_pk_fma_f32 v[10:11], v[10:11], v[230:231], v[94:95]
	ds_read_b128 v[228:231], v40 offset:7680
	s_waitcnt lgkmcnt(5)
	v_pk_mul_f32 v[88:89], v[12:13], v[224:225]
	v_pk_fma_f32 v[88:89], v[10:11], v[226:227], v[88:89]
	v_add_f32_e32 v90, v88, v89
	v_pk_mul_f32 v[92:93], v[108:109], v[240:241] op_sel:[1,0] op_sel_hi:[1,1]
	v_pk_mul_f32 v[94:95], v[108:109], v[242:243] op_sel:[1,0] op_sel_hi:[1,1]
	v_add_f32_dpp v90, v90, v90 row_ror:8 row_mask:0xf bank_mask:0xf bound_ctrl:1
	ds_read_b128 v[224:227], v40 offset:20224
	ds_read_b128 v[240:243], v40 offset:12032
	v_add_f32_dpp v90, v90, v90 row_ror:4 row_mask:0xf bank_mask:0xf bound_ctrl:1
	v_pk_mul_f32 v[100:101], v[12:13], v[100:101]
	v_pk_fma_f32 v[100:101], v[10:11], v[102:103], v[100:101]
	v_add_f32_dpp v90, v90, v90 row_ror:2 row_mask:0xf bank_mask:0xf bound_ctrl:1
	v_add_f32_e32 v0, v100, v101
	ds_read_b128 v[100:103], v40 offset:3584
	v_add_f32_dpp v90, v90, v90 row_ror:1 row_mask:0xf bank_mask:0xf bound_ctrl:1
	v_pk_fma_f32 v[92:93], v[90:91], v[248:249], v[92:93] op_sel_hi:[0,1,1]
	v_pk_fma_f32 v[94:95], v[90:91], v[250:251], v[94:95] op_sel_hi:[0,1,1]
	ds_read_b128 v[248:251], v40 offset:24320
	v_pk_fma_f32 v[12:13], v[12:13], v[232:233], v[92:93]
	v_pk_fma_f32 v[10:11], v[10:11], v[234:235], v[94:95]
	ds_read_b128 v[232:235], v40 offset:7936
	s_waitcnt lgkmcnt(5)
	v_pk_mul_f32 v[88:89], v[12:13], v[220:221]
	v_pk_fma_f32 v[88:89], v[10:11], v[222:223], v[88:89]
	v_add_f32_e32 v90, v88, v89
	v_pk_mul_f32 v[92:93], v[110:111], v[236:237] op_sel_hi:[0,1]
	v_pk_mul_f32 v[94:95], v[110:111], v[238:239] op_sel_hi:[0,1]
	v_add_f32_dpp v90, v90, v90 row_ror:8 row_mask:0xf bank_mask:0xf bound_ctrl:1
	s_nop 1
	v_add_f32_dpp v90, v90, v90 row_ror:4 row_mask:0xf bank_mask:0xf bound_ctrl:1
	v_pk_mul_f32 v[104:105], v[12:13], v[104:105]
	v_pk_fma_f32 v[104:105], v[10:11], v[106:107], v[104:105]
	v_add_f32_dpp v90, v90, v90 row_ror:2 row_mask:0xf bank_mask:0xf bound_ctrl:1
	v_add_f32_e32 v84, v104, v105
	ds_read_b128 v[104:107], v40 offset:3840
	v_add_f32_dpp v90, v90, v90 row_ror:1 row_mask:0xf bank_mask:0xf bound_ctrl:1
	v_pk_fma_f32 v[92:93], v[90:91], v[244:245], v[92:93] op_sel_hi:[0,1,1]
	v_pk_fma_f32 v[94:95], v[90:91], v[246:247], v[94:95] op_sel_hi:[0,1,1]
	v_pk_fma_f32 v[12:13], v[12:13], v[228:229], v[92:93]
	v_pk_fma_f32 v[10:11], v[10:11], v[230:231], v[94:95]
	s_waitcnt lgkmcnt(1)
	v_pk_mul_f32 v[88:89], v[12:13], v[224:225]
	v_pk_fma_f32 v[88:89], v[10:11], v[226:227], v[88:89]
	v_add_f32_e32 v90, v88, v89
	v_pk_mul_f32 v[92:93], v[110:111], v[240:241] op_sel:[1,0] op_sel_hi:[1,1]
	v_pk_mul_f32 v[94:95], v[110:111], v[242:243] op_sel:[1,0] op_sel_hi:[1,1]
	v_add_f32_dpp v90, v90, v90 row_ror:8 row_mask:0xf bank_mask:0xf bound_ctrl:1
	s_nop 1
	v_add_f32_dpp v90, v90, v90 row_ror:4 row_mask:0xf bank_mask:0xf bound_ctrl:1
	v_pk_mul_f32 v[100:101], v[12:13], v[100:101]
	v_pk_fma_f32 v[100:101], v[10:11], v[102:103], v[100:101]
	v_add_f32_dpp v90, v90, v90 row_ror:2 row_mask:0xf bank_mask:0xf bound_ctrl:1
	v_add_f32_e32 v85, v100, v101
	s_nop 0
	v_add_f32_dpp v90, v90, v90 row_ror:1 row_mask:0xf bank_mask:0xf bound_ctrl:1
	v_pk_fma_f32 v[92:93], v[90:91], v[248:249], v[92:93] op_sel_hi:[0,1,1]
	v_pk_fma_f32 v[94:95], v[90:91], v[250:251], v[94:95] op_sel_hi:[0,1,1]
	v_pk_fma_f32 v[12:13], v[12:13], v[232:233], v[92:93]
	v_pk_fma_f32 v[10:11], v[10:11], v[234:235], v[94:95]
	s_waitcnt lgkmcnt(0)
	v_pk_mul_f32 v[104:105], v[12:13], v[104:105]
	v_pk_fma_f32 v[104:105], v[10:11], v[106:107], v[104:105]
	v_add_f32_dpp v96, v96, v96 row_mirror row_mask:0xf bank_mask:0x3
	v_add_f32_dpp v96, v187, v187 row_mirror row_mask:0xf bank_mask:0xc
	v_add_f32_e32 v86, v104, v105
	v_add_f32_dpp v97, v97, v97 row_mirror row_mask:0xf bank_mask:0x3
	v_add_f32_dpp v97, v190, v190 row_mirror row_mask:0xf bank_mask:0xc
	v_add_f32_dpp v98, v98, v98 row_mirror row_mask:0xf bank_mask:0x3
	v_add_f32_dpp v98, v191, v191 row_mirror row_mask:0xf bank_mask:0xc
	v_add_f32_dpp v99, v99, v99 row_mirror row_mask:0xf bank_mask:0x3
	v_add_f32_dpp v99, v200, v200 row_mirror row_mask:0xf bank_mask:0xc
	v_add_f32_dpp v87, v87, v87 row_mirror row_mask:0xf bank_mask:0x3
	v_add_f32_dpp v87, v0, v0 row_mirror row_mask:0xf bank_mask:0xc
	v_add_f32_dpp v217, v217, v217 row_mirror row_mask:0xf bank_mask:0x3
	v_add_f32_dpp v217, v84, v84 row_mirror row_mask:0xf bank_mask:0xc
	v_add_f32_dpp v218, v218, v218 row_mirror row_mask:0xf bank_mask:0x3
	v_add_f32_dpp v218, v85, v85 row_mirror row_mask:0xf bank_mask:0xc
	v_add_f32_dpp v219, v219, v219 row_mirror row_mask:0xf bank_mask:0x3
	v_add_f32_dpp v219, v86, v86 row_mirror row_mask:0xf bank_mask:0xc
	v_add_f32_dpp v96, v96, v96 row_half_mirror row_mask:0xf bank_mask:0x5
	v_add_f32_dpp v96, v87, v87 row_half_mirror row_mask:0xf bank_mask:0xa
	v_add_f32_dpp v97, v97, v97 row_half_mirror row_mask:0xf bank_mask:0x5
	v_add_f32_dpp v97, v217, v217 row_half_mirror row_mask:0xf bank_mask:0xa
	v_add_f32_dpp v98, v98, v98 row_half_mirror row_mask:0xf bank_mask:0x5
	v_add_f32_dpp v98, v218, v218 row_half_mirror row_mask:0xf bank_mask:0xa
	v_add_f32_dpp v99, v99, v99 row_half_mirror row_mask:0xf bank_mask:0x5
	v_add_f32_dpp v99, v219, v219 row_half_mirror row_mask:0xf bank_mask:0xa
	s_mov_b32 vcc_lo, 0xcccccccc
	s_mov_b32 vcc_hi, 0xcccccccc
	v_cndmask_b32_e32 v187, v96, v98, vcc
	v_cndmask_b32_e32 v190, v98, v96, vcc
	v_cndmask_b32_e32 v200, v99, v97, vcc
	v_cndmask_b32_e32 v191, v97, v99, vcc
	v_add_f32_dpp v0, v190, v187 quad_perm:[2,3,0,1] row_mask:0xf bank_mask:0xf bound_ctrl:1
	v_add_f32_dpp v84, v200, v191 quad_perm:[2,3,0,1] row_mask:0xf bank_mask:0xf bound_ctrl:1
	s_mov_b32 vcc_lo, 0xaaaaaaaa
	s_mov_b32 vcc_hi, 0xaaaaaaaa
	v_cndmask_b32_e32 v85, v0, v84, vcc
	v_cndmask_b32_e32 v86, v84, v0, vcc
	s_nop 1
	v_add_f32_dpp v86, v86, v85 quad_perm:[1,0,3,2] row_mask:0xf bank_mask:0xf bound_ctrl:1
	v_lshl_or_b32 v84, s4, 4, v31
	v_or_b32_e32 v84, s56, v84
	v_mov_b32_e32 v85, s57
	s_waitcnt vmcnt(38)
	v_lshlrev_b32_e32 v15, 16, v15
	v_lshlrev_b64 v[84:85], 10, v[84:85]
	v_mul_f32_e32 v15, 0x3fb8aa3b, v15
	v_cvt_pk_bf16_f32 v0, v86, s0
	v_lshl_add_u64 v[84:85], v[6:7], 0, v[84:85]
	v_lshlrev_b32_e32 v75, 16, v75
	v_lshlrev_b32_e32 v78, 16, v78
	v_exp_f32_e32 v15, v15
	s_waitcnt vmcnt(37)
	v_lshlrev_b32_e32 v43, 16, v43
	global_store_short v[84:85], v0, off
	v_sub_f32_e32 v78, v78, v75
	v_add_f32_e32 v84, -1.0, v43
	v_lshlrev_b32_e32 v81, 16, v81
	v_lshlrev_b32_e32 v79, 16, v79
	v_fma_f32 v78, v16, v78, v75
	v_fma_f32 v84, v19, v84, 1.0
	v_lshlrev_b32_e32 v0, 16, v82
	v_sub_f32_e32 v79, v79, v81
	v_mul_f32_e32 v82, v18, v78
	v_mul_f32_e32 v78, v78, v84
	v_fma_f32 v79, v17, v79, v81
	ds_write2st64_b32 v32, v15, v78 offset0:112 offset1:128
	s_waitcnt vmcnt(37)
	v_mul_f32_e64 v15, v82, -v44
	s_waitcnt vmcnt(36)
	v_lshlrev_b32_e32 v48, 16, v48
	v_lshlrev_b32_e32 v80, 16, v80
	ds_write2st64_b32 v32, v79, v15 offset0:144 offset1:160
	v_mul_f32_e64 v15, -v15, v43
	v_lshlrev_b32_e32 v43, 16, v74
	v_mul_f32_e32 v48, 0x3fb8aa3b, v48
	v_sub_f32_e32 v80, v80, v0
	ds_write_b32 v32, v15 offset:45056
	v_lshlrev_b32_e32 v15, 16, v76
	v_sub_f32_e32 v74, v75, v43
	v_exp_f32_e32 v48, v48
	s_waitcnt vmcnt(35)
	v_lshlrev_b32_e32 v49, 16, v49
	v_fma_f32 v80, v3, v80, v0
	v_lshlrev_b32_e32 v44, 16, v77
	v_sub_f32_e32 v0, v0, v15
	v_fma_f32 v74, v16, v74, v43
	v_add_f32_e32 v77, -1.0, v49
	v_fma_f32 v0, v3, v0, v15
	v_sub_f32_e32 v75, v81, v44
	v_mul_f32_e32 v76, v18, v74
	v_fma_f32 v77, v19, v77, 1.0
	v_fma_f32 v75, v17, v75, v44
	v_mul_f32_e32 v74, v74, v77
	ds_write2st64_b32 v32, v80, v0 offset0:96 offset1:97
	ds_write_b32 v33, v48 offset:24832
	ds_write_b32 v34, v74 offset:24832
	ds_write_b32 v35, v75 offset:24832
	s_waitcnt vmcnt(34)
	v_mul_f32_e64 v0, v76, -v46
	s_waitcnt vmcnt(33)
	v_lshlrev_b32_e32 v45, 16, v45
	ds_write_b32 v36, v0 offset:24832
	v_mul_f32_e64 v0, -v0, v49
	v_lshlrev_b32_e32 v46, 16, v69
	v_mul_f32_e32 v45, 0x3fb8aa3b, v45
	ds_write_b32 v37, v0 offset:24832
	v_lshlrev_b32_e32 v0, 16, v72
	v_sub_f32_e32 v43, v43, v46
	v_exp_f32_e32 v45, v45
	s_waitcnt vmcnt(32)
	v_lshlrev_b32_e32 v47, 16, v47
	v_lshlrev_b32_e32 v48, 16, v73
	v_sub_f32_e32 v15, v15, v0
	v_fma_f32 v43, v16, v43, v46
	v_add_f32_e32 v69, -1.0, v47
	v_fma_f32 v15, v3, v15, v0
	v_sub_f32_e32 v44, v44, v48
	v_mul_f32_e32 v49, v18, v43
	v_fma_f32 v69, v19, v69, 1.0
	v_fma_f32 v44, v17, v44, v48
	v_mul_f32_e32 v43, v43, v69
	ds_write_b32 v32, v15 offset:25088
	ds_write_b32 v33, v45 offset:25088
	ds_write_b32 v34, v43 offset:25088
	ds_write_b32 v35, v44 offset:25088
	s_waitcnt vmcnt(31)
	v_mul_f32_e64 v15, v49, -v52
	ds_write_b32 v36, v15 offset:25088
	v_mul_f32_e64 v15, -v15, v47
	ds_write_b32 v37, v15 offset:25088
	v_lshlrev_b32_e32 v15, 16, v70
	v_lshlrev_b32_e32 v14, 16, v14
	v_sub_f32_e32 v0, v0, v15
	v_lshlrev_b32_e32 v43, 16, v71
	v_fmac_f32_e32 v15, v3, v0
	v_sub_f32_e32 v0, v46, v14
	v_fmac_f32_e32 v14, v16, v0
	v_sub_f32_e32 v0, v48, v43
	v_fmac_f32_e32 v43, v17, v0
	s_waitcnt vmcnt(30)
	v_lshlrev_b32_e32 v0, 16, v50
	v_mul_f32_e32 v0, 0x3fb8aa3b, v0
	v_exp_f32_e32 v0, v0
	s_waitcnt vmcnt(29)
	v_lshlrev_b32_e32 v44, 16, v51
	v_add_f32_e32 v46, -1.0, v44
	s_or_b32 s5, s4, 1
	v_mul_f32_e32 v45, v18, v14
	v_fma_f32 v46, v19, v46, 1.0
	v_mul_f32_e32 v14, v14, v46
	ds_write_b32 v32, v15 offset:25344
	ds_write_b32 v33, v0 offset:25344
	ds_write_b32 v34, v14 offset:25344
	ds_write_b32 v35, v43 offset:25344
	s_waitcnt vmcnt(28)
	v_mul_f32_e64 v0, v45, -v53
	s_min_u32 s6, s5, 0xfd
	ds_write_b32 v36, v0 offset:25344
	v_mul_f32_e64 v0, -v0, v44
	v_lshl_add_u32 v14, s6, 4, v38
	ds_write_b32 v37, v0 offset:25344
	v_max_i32_e32 v0, 1, v14
	v_add_u32_e32 v0, -1, v0
	v_lshl_add_u64 v[44:45], s[56:57], 0, v[0:1]
	v_mad_u64_u32 v[46:47], s[6:7], v44, s29, v[4:5]
	v_mad_i32_i24 v47, v45, s29, v47
	s_waitcnt lgkmcnt(0)
	s_barrier
	ds_read_b128 v[220:223], v42 offset:16384
	ds_read_b128 v[236:239], v42 offset:8192
	ds_read2st64_b32 v[108:109], v41 offset0:0 offset1:1
	ds_read_b128 v[244:247], v42 offset:20480
	ds_read_b128 v[228:231], v42 offset:4096
	ds_read_b128 v[100:103], v42 offset:0
	ds_read_b128 v[224:227], v42 offset:16640
	ds_read_b128 v[240:243], v42 offset:8448
	ds_read2st64_b32 v[110:111], v41 offset0:2 offset1:3
	ds_read_b128 v[248:251], v42 offset:20736
	ds_read_b128 v[232:235], v42 offset:4352
	s_mov_b64 s[6:7], 0xd00
	global_load_ushort v70, v[46:47], off
	global_load_ushort v72, v[46:47], off offset:1024
	global_load_ushort v71, v[46:47], off offset:2048
	v_lshl_add_u64 v[112:113], v[46:47], 0, s[6:7]
	v_lshl_add_u64 v[114:115], v[112:113], 0, s[6:7]
	v_lshl_add_u64 v[116:117], v[114:115], 0, s[6:7]
	v_lshl_add_u64 v[118:119], v[116:117], 0, s[6:7]
	v_ashrrev_i32_e32 v15, 31, v14
	v_lshl_add_u64 v[120:121], s[56:57], 0, v[14:15]
	v_lshlrev_b64 v[122:123], 10, v[120:121]
	v_or_b32_e32 v122, v122, v83
	v_lshl_add_u64 v[124:125], s[0:1], 0, v[122:123]
	v_lshl_add_u64 v[126:127], s[24:25], 0, v[122:123]
	v_lshlrev_b64 v[128:129], 5, v[120:121]
	v_lshl_add_u64 v[128:129], s[58:59], 0, v[128:129]
	global_load_ushort v73, v[112:113], off
	global_load_ushort v69, v[112:113], off offset:1024
	global_load_ushort v76, v[112:113], off offset:2048
	global_load_ushort v77, v[114:115], off
	global_load_ushort v74, v[114:115], off offset:1024
	global_load_ushort v84, v[114:115], off offset:2048
	global_load_ushort v78, v[116:117], off offset:1024
	global_load_ushort v85, v[116:117], off offset:2048
	global_load_ushort v15, v[124:125], off
	global_load_ushort v43, v[126:127], off
	global_load_dword v44, v[128:129], off
	global_load_ushort v48, v[124:125], off offset:1024
	global_load_ushort v49, v[126:127], off offset:1024
	global_load_dword v46, v[128:129], off offset:32
	global_load_ushort v45, v[124:125], off offset:2048
	global_load_ushort v47, v[126:127], off offset:2048
	global_load_ushort v83, v[116:117], off
	global_load_ushort v0, v[118:119], off
	global_load_ushort v79, v[118:119], off offset:1024
	global_load_ushort v86, v[118:119], off offset:2048
	global_load_dword v52, v[128:129], off offset:64
	global_load_ushort v50, v[124:125], off offset:3072
	global_load_ushort v51, v[126:127], off offset:3072
	global_load_dword v53, v[128:129], off offset:96
	s_mov_b32 s6, 0
	v_mov_b32_e32 v87, 0
	v_mov_b32_e32 v75, v31
	v_mov_b32_e32 v80, v42
	v_mov_b32_e32 v81, v41
	s_waitcnt lgkmcnt(6)
	v_pk_mul_f32 v[88:89], v[12:13], v[220:221]
	v_pk_fma_f32 v[88:89], v[10:11], v[222:223], v[88:89]
	v_add_f32_e32 v90, v88, v89
	v_pk_mul_f32 v[92:93], v[108:109], v[236:237] op_sel_hi:[0,1]
	v_pk_mul_f32 v[94:95], v[108:109], v[238:239] op_sel_hi:[0,1]
	v_add_f32_dpp v90, v90, v90 row_ror:8 row_mask:0xf bank_mask:0xf bound_ctrl:1
	ds_read_b128 v[220:223], v42 offset:16896
	ds_read_b128 v[236:239], v42 offset:8704
	v_add_f32_dpp v90, v90, v90 row_ror:4 row_mask:0xf bank_mask:0xf bound_ctrl:1
	s_nop 1
	v_add_f32_dpp v90, v90, v90 row_ror:2 row_mask:0xf bank_mask:0xf bound_ctrl:1
	ds_read_b128 v[104:107], v42 offset:256
	s_nop 0
	v_add_f32_dpp v90, v90, v90 row_ror:1 row_mask:0xf bank_mask:0xf bound_ctrl:1
	v_pk_fma_f32 v[92:93], v[90:91], v[244:245], v[92:93] op_sel_hi:[0,1,1]
	v_pk_fma_f32 v[94:95], v[90:91], v[246:247], v[94:95] op_sel_hi:[0,1,1]
	ds_read_b128 v[244:247], v42 offset:20992
	v_pk_fma_f32 v[12:13], v[12:13], v[228:229], v[92:93]
	v_pk_fma_f32 v[10:11], v[10:11], v[230:231], v[94:95]
	ds_read_b128 v[228:231], v42 offset:4608
	s_waitcnt lgkmcnt(5)
	v_pk_mul_f32 v[88:89], v[12:13], v[224:225]
	v_pk_fma_f32 v[88:89], v[10:11], v[226:227], v[88:89]
	v_add_f32_e32 v90, v88, v89
	v_pk_mul_f32 v[92:93], v[108:109], v[240:241] op_sel:[1,0] op_sel_hi:[1,1]
	v_pk_mul_f32 v[94:95], v[108:109], v[242:243] op_sel:[1,0] op_sel_hi:[1,1]
	v_add_f32_dpp v90, v90, v90 row_ror:8 row_mask:0xf bank_mask:0xf bound_ctrl:1
	ds_read_b128 v[224:227], v42 offset:17152
	ds_read_b128 v[240:243], v42 offset:8960
	v_add_f32_dpp v90, v90, v90 row_ror:4 row_mask:0xf bank_mask:0xf bound_ctrl:1
	v_pk_mul_f32 v[100:101], v[12:13], v[100:101]
	v_pk_fma_f32 v[100:101], v[10:11], v[102:103], v[100:101]
	v_add_f32_dpp v90, v90, v90 row_ror:2 row_mask:0xf bank_mask:0xf bound_ctrl:1
	v_add_f32_e32 v96, v100, v101
	ds_read_b128 v[100:103], v42 offset:512
	v_add_f32_dpp v90, v90, v90 row_ror:1 row_mask:0xf bank_mask:0xf bound_ctrl:1
	ds_read2st64_b32 v[108:109], v41 offset0:4 offset1:5
	v_pk_fma_f32 v[92:93], v[90:91], v[248:249], v[92:93] op_sel_hi:[0,1,1]
	v_pk_fma_f32 v[94:95], v[90:91], v[250:251], v[94:95] op_sel_hi:[0,1,1]
	ds_read_b128 v[248:251], v42 offset:21248
	v_pk_fma_f32 v[12:13], v[12:13], v[232:233], v[92:93]
	v_pk_fma_f32 v[10:11], v[10:11], v[234:235], v[94:95]
	ds_read_b128 v[232:235], v42 offset:4864
	s_waitcnt lgkmcnt(6)
	v_pk_mul_f32 v[88:89], v[12:13], v[220:221]
	v_pk_fma_f32 v[88:89], v[10:11], v[222:223], v[88:89]
	v_add_f32_e32 v90, v88, v89
	v_pk_mul_f32 v[92:93], v[110:111], v[236:237] op_sel_hi:[0,1]
	v_pk_mul_f32 v[94:95], v[110:111], v[238:239] op_sel_hi:[0,1]
	v_add_f32_dpp v90, v90, v90 row_ror:8 row_mask:0xf bank_mask:0xf bound_ctrl:1
	ds_read_b128 v[220:223], v42 offset:17408
	ds_read_b128 v[236:239], v42 offset:9216
	v_add_f32_dpp v90, v90, v90 row_ror:4 row_mask:0xf bank_mask:0xf bound_ctrl:1
	v_pk_mul_f32 v[104:105], v[12:13], v[104:105]
	v_pk_fma_f32 v[104:105], v[10:11], v[106:107], v[104:105]
	v_add_f32_dpp v90, v90, v90 row_ror:2 row_mask:0xf bank_mask:0xf bound_ctrl:1
	v_add_f32_e32 v97, v104, v105
	ds_read_b128 v[104:107], v42 offset:768
	v_add_f32_dpp v90, v90, v90 row_ror:1 row_mask:0xf bank_mask:0xf bound_ctrl:1
	v_pk_fma_f32 v[92:93], v[90:91], v[244:245], v[92:93] op_sel_hi:[0,1,1]
	v_pk_fma_f32 v[94:95], v[90:91], v[246:247], v[94:95] op_sel_hi:[0,1,1]
	ds_read_b128 v[244:247], v42 offset:21504
	v_pk_fma_f32 v[12:13], v[12:13], v[228:229], v[92:93]
	v_pk_fma_f32 v[10:11], v[10:11], v[230:231], v[94:95]
	ds_read_b128 v[228:231], v42 offset:5120
	s_waitcnt lgkmcnt(5)
	v_pk_mul_f32 v[88:89], v[12:13], v[224:225]
	v_pk_fma_f32 v[88:89], v[10:11], v[226:227], v[88:89]
	v_add_f32_e32 v90, v88, v89
	v_pk_mul_f32 v[92:93], v[110:111], v[240:241] op_sel:[1,0] op_sel_hi:[1,1]
	v_pk_mul_f32 v[94:95], v[110:111], v[242:243] op_sel:[1,0] op_sel_hi:[1,1]
	v_add_f32_dpp v90, v90, v90 row_ror:8 row_mask:0xf bank_mask:0xf bound_ctrl:1
	ds_read_b128 v[224:227], v42 offset:17664
	ds_read_b128 v[240:243], v42 offset:9472
	v_add_f32_dpp v90, v90, v90 row_ror:4 row_mask:0xf bank_mask:0xf bound_ctrl:1
	v_pk_mul_f32 v[100:101], v[12:13], v[100:101]
	v_pk_fma_f32 v[100:101], v[10:11], v[102:103], v[100:101]
	v_add_f32_dpp v90, v90, v90 row_ror:2 row_mask:0xf bank_mask:0xf bound_ctrl:1
	v_add_f32_e32 v98, v100, v101
	ds_read_b128 v[100:103], v42 offset:1024
	v_add_f32_dpp v90, v90, v90 row_ror:1 row_mask:0xf bank_mask:0xf bound_ctrl:1
	ds_read2st64_b32 v[110:111], v41 offset0:6 offset1:7
	v_pk_fma_f32 v[92:93], v[90:91], v[248:249], v[92:93] op_sel_hi:[0,1,1]
	v_pk_fma_f32 v[94:95], v[90:91], v[250:251], v[94:95] op_sel_hi:[0,1,1]
	ds_read_b128 v[248:251], v42 offset:21760
	v_pk_fma_f32 v[12:13], v[12:13], v[232:233], v[92:93]
	v_pk_fma_f32 v[10:11], v[10:11], v[234:235], v[94:95]
	ds_read_b128 v[232:235], v42 offset:5376
	s_waitcnt lgkmcnt(6)
	v_pk_mul_f32 v[88:89], v[12:13], v[220:221]
	v_pk_fma_f32 v[88:89], v[10:11], v[222:223], v[88:89]
	v_add_f32_e32 v90, v88, v89
	v_pk_mul_f32 v[92:93], v[108:109], v[236:237] op_sel_hi:[0,1]
	v_pk_mul_f32 v[94:95], v[108:109], v[238:239] op_sel_hi:[0,1]
	v_add_f32_dpp v90, v90, v90 row_ror:8 row_mask:0xf bank_mask:0xf bound_ctrl:1
	ds_read_b128 v[220:223], v42 offset:17920
	ds_read_b128 v[236:239], v42 offset:9728
	v_add_f32_dpp v90, v90, v90 row_ror:4 row_mask:0xf bank_mask:0xf bound_ctrl:1
	v_pk_mul_f32 v[104:105], v[12:13], v[104:105]
	v_pk_fma_f32 v[104:105], v[10:11], v[106:107], v[104:105]
	v_add_f32_dpp v90, v90, v90 row_ror:2 row_mask:0xf bank_mask:0xf bound_ctrl:1
	v_add_f32_e32 v99, v104, v105
	ds_read_b128 v[104:107], v42 offset:1280
	v_add_f32_dpp v90, v90, v90 row_ror:1 row_mask:0xf bank_mask:0xf bound_ctrl:1
	v_pk_fma_f32 v[92:93], v[90:91], v[244:245], v[92:93] op_sel_hi:[0,1,1]
	v_pk_fma_f32 v[94:95], v[90:91], v[246:247], v[94:95] op_sel_hi:[0,1,1]
	ds_read_b128 v[244:247], v42 offset:22016
	v_pk_fma_f32 v[12:13], v[12:13], v[228:229], v[92:93]
	v_pk_fma_f32 v[10:11], v[10:11], v[230:231], v[94:95]
	ds_read_b128 v[228:231], v42 offset:5632
	s_waitcnt lgkmcnt(5)
	v_pk_mul_f32 v[88:89], v[12:13], v[224:225]
	v_pk_fma_f32 v[88:89], v[10:11], v[226:227], v[88:89]
	v_add_f32_e32 v90, v88, v89
	v_pk_mul_f32 v[92:93], v[108:109], v[240:241] op_sel:[1,0] op_sel_hi:[1,1]
	v_pk_mul_f32 v[94:95], v[108:109], v[242:243] op_sel:[1,0] op_sel_hi:[1,1]
	v_add_f32_dpp v90, v90, v90 row_ror:8 row_mask:0xf bank_mask:0xf bound_ctrl:1
	ds_read_b128 v[224:227], v42 offset:18176
	ds_read_b128 v[240:243], v42 offset:9984
	v_add_f32_dpp v90, v90, v90 row_ror:4 row_mask:0xf bank_mask:0xf bound_ctrl:1
	v_pk_mul_f32 v[100:101], v[12:13], v[100:101]
	v_pk_fma_f32 v[100:101], v[10:11], v[102:103], v[100:101]
	v_add_f32_dpp v90, v90, v90 row_ror:2 row_mask:0xf bank_mask:0xf bound_ctrl:1
	v_add_f32_e32 v87, v100, v101
	ds_read_b128 v[100:103], v42 offset:1536
	v_add_f32_dpp v90, v90, v90 row_ror:1 row_mask:0xf bank_mask:0xf bound_ctrl:1
	ds_read2st64_b32 v[108:109], v41 offset0:8 offset1:9
	v_pk_fma_f32 v[92:93], v[90:91], v[248:249], v[92:93] op_sel_hi:[0,1,1]
	v_pk_fma_f32 v[94:95], v[90:91], v[250:251], v[94:95] op_sel_hi:[0,1,1]
	ds_read_b128 v[248:251], v42 offset:22272
	v_pk_fma_f32 v[12:13], v[12:13], v[232:233], v[92:93]
	v_pk_fma_f32 v[10:11], v[10:11], v[234:235], v[94:95]
	ds_read_b128 v[232:235], v42 offset:5888
	s_waitcnt lgkmcnt(6)
	v_pk_mul_f32 v[88:89], v[12:13], v[220:221]
	v_pk_fma_f32 v[88:89], v[10:11], v[222:223], v[88:89]
	v_add_f32_e32 v90, v88, v89
	v_pk_mul_f32 v[92:93], v[110:111], v[236:237] op_sel_hi:[0,1]
	v_pk_mul_f32 v[94:95], v[110:111], v[238:239] op_sel_hi:[0,1]
	v_add_f32_dpp v90, v90, v90 row_ror:8 row_mask:0xf bank_mask:0xf bound_ctrl:1
	ds_read_b128 v[220:223], v42 offset:18432
	ds_read_b128 v[236:239], v42 offset:10240
	v_add_f32_dpp v90, v90, v90 row_ror:4 row_mask:0xf bank_mask:0xf bound_ctrl:1
	v_pk_mul_f32 v[104:105], v[12:13], v[104:105]
	v_pk_fma_f32 v[104:105], v[10:11], v[106:107], v[104:105]
	v_add_f32_dpp v90, v90, v90 row_ror:2 row_mask:0xf bank_mask:0xf bound_ctrl:1
	v_add_f32_e32 v217, v104, v105
	ds_read_b128 v[104:107], v42 offset:1792
	v_add_f32_dpp v90, v90, v90 row_ror:1 row_mask:0xf bank_mask:0xf bound_ctrl:1
	v_pk_fma_f32 v[92:93], v[90:91], v[244:245], v[92:93] op_sel_hi:[0,1,1]
	v_pk_fma_f32 v[94:95], v[90:91], v[246:247], v[94:95] op_sel_hi:[0,1,1]
	ds_read_b128 v[244:247], v42 offset:22528
	v_pk_fma_f32 v[12:13], v[12:13], v[228:229], v[92:93]
	v_pk_fma_f32 v[10:11], v[10:11], v[230:231], v[94:95]
	ds_read_b128 v[228:231], v42 offset:6144
	s_waitcnt lgkmcnt(5)
	v_pk_mul_f32 v[88:89], v[12:13], v[224:225]
	v_pk_fma_f32 v[88:89], v[10:11], v[226:227], v[88:89]
	v_add_f32_e32 v90, v88, v89
	v_pk_mul_f32 v[92:93], v[110:111], v[240:241] op_sel:[1,0] op_sel_hi:[1,1]
	v_pk_mul_f32 v[94:95], v[110:111], v[242:243] op_sel:[1,0] op_sel_hi:[1,1]
	v_add_f32_dpp v90, v90, v90 row_ror:8 row_mask:0xf bank_mask:0xf bound_ctrl:1
	ds_read_b128 v[224:227], v42 offset:18688
	ds_read_b128 v[240:243], v42 offset:10496
	v_add_f32_dpp v90, v90, v90 row_ror:4 row_mask:0xf bank_mask:0xf bound_ctrl:1
	v_pk_mul_f32 v[100:101], v[12:13], v[100:101]
	v_pk_fma_f32 v[100:101], v[10:11], v[102:103], v[100:101]
	v_add_f32_dpp v90, v90, v90 row_ror:2 row_mask:0xf bank_mask:0xf bound_ctrl:1
	v_add_f32_e32 v218, v100, v101
	ds_read_b128 v[100:103], v42 offset:2048
	v_add_f32_dpp v90, v90, v90 row_ror:1 row_mask:0xf bank_mask:0xf bound_ctrl:1
	ds_read2st64_b32 v[110:111], v41 offset0:10 offset1:11
	v_pk_fma_f32 v[92:93], v[90:91], v[248:249], v[92:93] op_sel_hi:[0,1,1]
	v_pk_fma_f32 v[94:95], v[90:91], v[250:251], v[94:95] op_sel_hi:[0,1,1]
	ds_read_b128 v[248:251], v42 offset:22784
	v_pk_fma_f32 v[12:13], v[12:13], v[232:233], v[92:93]
	v_pk_fma_f32 v[10:11], v[10:11], v[234:235], v[94:95]
	ds_read_b128 v[232:235], v42 offset:6400
	s_waitcnt lgkmcnt(6)
	v_pk_mul_f32 v[88:89], v[12:13], v[220:221]
	v_pk_fma_f32 v[88:89], v[10:11], v[222:223], v[88:89]
	v_add_f32_e32 v90, v88, v89
	v_pk_mul_f32 v[92:93], v[108:109], v[236:237] op_sel_hi:[0,1]
	v_pk_mul_f32 v[94:95], v[108:109], v[238:239] op_sel_hi:[0,1]
	v_add_f32_dpp v90, v90, v90 row_ror:8 row_mask:0xf bank_mask:0xf bound_ctrl:1
	ds_read_b128 v[220:223], v42 offset:18944
	ds_read_b128 v[236:239], v42 offset:10752
	v_add_f32_dpp v90, v90, v90 row_ror:4 row_mask:0xf bank_mask:0xf bound_ctrl:1
	v_pk_mul_f32 v[104:105], v[12:13], v[104:105]
	v_pk_fma_f32 v[104:105], v[10:11], v[106:107], v[104:105]
	v_add_f32_dpp v90, v90, v90 row_ror:2 row_mask:0xf bank_mask:0xf bound_ctrl:1
	v_add_f32_e32 v219, v104, v105
	ds_read_b128 v[104:107], v42 offset:2304
	v_add_f32_dpp v90, v90, v90 row_ror:1 row_mask:0xf bank_mask:0xf bound_ctrl:1
	v_pk_fma_f32 v[92:93], v[90:91], v[244:245], v[92:93] op_sel_hi:[0,1,1]
	v_pk_fma_f32 v[94:95], v[90:91], v[246:247], v[94:95] op_sel_hi:[0,1,1]
	ds_read_b128 v[244:247], v42 offset:23040
	v_pk_fma_f32 v[12:13], v[12:13], v[228:229], v[92:93]
	v_pk_fma_f32 v[10:11], v[10:11], v[230:231], v[94:95]
	ds_read_b128 v[228:231], v42 offset:6656
	s_waitcnt lgkmcnt(5)
	v_pk_mul_f32 v[88:89], v[12:13], v[224:225]
	v_pk_fma_f32 v[88:89], v[10:11], v[226:227], v[88:89]
	v_add_f32_e32 v90, v88, v89
	v_pk_mul_f32 v[92:93], v[108:109], v[240:241] op_sel:[1,0] op_sel_hi:[1,1]
	v_pk_mul_f32 v[94:95], v[108:109], v[242:243] op_sel:[1,0] op_sel_hi:[1,1]
	v_add_f32_dpp v90, v90, v90 row_ror:8 row_mask:0xf bank_mask:0xf bound_ctrl:1
	ds_read_b128 v[224:227], v42 offset:19200
	ds_read_b128 v[240:243], v42 offset:11008
	v_add_f32_dpp v90, v90, v90 row_ror:4 row_mask:0xf bank_mask:0xf bound_ctrl:1
	v_pk_mul_f32 v[100:101], v[12:13], v[100:101]
	v_pk_fma_f32 v[100:101], v[10:11], v[102:103], v[100:101]
	v_add_f32_dpp v90, v90, v90 row_ror:2 row_mask:0xf bank_mask:0xf bound_ctrl:1
	v_add_f32_e32 v187, v100, v101
	ds_read_b128 v[100:103], v42 offset:2560
	v_add_f32_dpp v90, v90, v90 row_ror:1 row_mask:0xf bank_mask:0xf bound_ctrl:1
	ds_read2st64_b32 v[108:109], v41 offset0:12 offset1:13
	v_pk_fma_f32 v[92:93], v[90:91], v[248:249], v[92:93] op_sel_hi:[0,1,1]
	v_pk_fma_f32 v[94:95], v[90:91], v[250:251], v[94:95] op_sel_hi:[0,1,1]
	ds_read_b128 v[248:251], v42 offset:23296
	v_pk_fma_f32 v[12:13], v[12:13], v[232:233], v[92:93]
	v_pk_fma_f32 v[10:11], v[10:11], v[234:235], v[94:95]
	ds_read_b128 v[232:235], v42 offset:6912
	s_waitcnt lgkmcnt(6)
	v_pk_mul_f32 v[88:89], v[12:13], v[220:221]
	v_pk_fma_f32 v[88:89], v[10:11], v[222:223], v[88:89]
	v_add_f32_e32 v90, v88, v89
	v_pk_mul_f32 v[92:93], v[110:111], v[236:237] op_sel_hi:[0,1]
	v_pk_mul_f32 v[94:95], v[110:111], v[238:239] op_sel_hi:[0,1]
	v_add_f32_dpp v90, v90, v90 row_ror:8 row_mask:0xf bank_mask:0xf bound_ctrl:1
	ds_read_b128 v[220:223], v42 offset:19456
	ds_read_b128 v[236:239], v42 offset:11264
	v_add_f32_dpp v90, v90, v90 row_ror:4 row_mask:0xf bank_mask:0xf bound_ctrl:1
	v_pk_mul_f32 v[104:105], v[12:13], v[104:105]
	v_pk_fma_f32 v[104:105], v[10:11], v[106:107], v[104:105]
	v_add_f32_dpp v90, v90, v90 row_ror:2 row_mask:0xf bank_mask:0xf bound_ctrl:1
	v_add_f32_e32 v190, v104, v105
	ds_read_b128 v[104:107], v42 offset:2816
	v_add_f32_dpp v90, v90, v90 row_ror:1 row_mask:0xf bank_mask:0xf bound_ctrl:1
	v_pk_fma_f32 v[92:93], v[90:91], v[244:245], v[92:93] op_sel_hi:[0,1,1]
	v_pk_fma_f32 v[94:95], v[90:91], v[246:247], v[94:95] op_sel_hi:[0,1,1]
	ds_read_b128 v[244:247], v42 offset:23552
	v_pk_fma_f32 v[12:13], v[12:13], v[228:229], v[92:93]
	v_pk_fma_f32 v[10:11], v[10:11], v[230:231], v[94:95]
	ds_read_b128 v[228:231], v42 offset:7168
	s_waitcnt lgkmcnt(5)
	v_pk_mul_f32 v[88:89], v[12:13], v[224:225]
	v_pk_fma_f32 v[88:89], v[10:11], v[226:227], v[88:89]
	v_add_f32_e32 v90, v88, v89
	v_pk_mul_f32 v[92:93], v[110:111], v[240:241] op_sel:[1,0] op_sel_hi:[1,1]
	v_pk_mul_f32 v[94:95], v[110:111], v[242:243] op_sel:[1,0] op_sel_hi:[1,1]
	v_add_f32_dpp v90, v90, v90 row_ror:8 row_mask:0xf bank_mask:0xf bound_ctrl:1
	ds_read_b128 v[224:227], v42 offset:19712
	ds_read_b128 v[240:243], v42 offset:11520
	v_add_f32_dpp v90, v90, v90 row_ror:4 row_mask:0xf bank_mask:0xf bound_ctrl:1
	v_pk_mul_f32 v[100:101], v[12:13], v[100:101]
	v_pk_fma_f32 v[100:101], v[10:11], v[102:103], v[100:101]
	v_add_f32_dpp v90, v90, v90 row_ror:2 row_mask:0xf bank_mask:0xf bound_ctrl:1
	v_add_f32_e32 v191, v100, v101
	ds_read_b128 v[100:103], v42 offset:3072
	v_add_f32_dpp v90, v90, v90 row_ror:1 row_mask:0xf bank_mask:0xf bound_ctrl:1
	ds_read2st64_b32 v[110:111], v41 offset0:14 offset1:15
	v_pk_fma_f32 v[92:93], v[90:91], v[248:249], v[92:93] op_sel_hi:[0,1,1]
	v_pk_fma_f32 v[94:95], v[90:91], v[250:251], v[94:95] op_sel_hi:[0,1,1]
	ds_read_b128 v[248:251], v42 offset:23808
	v_pk_fma_f32 v[12:13], v[12:13], v[232:233], v[92:93]
	v_pk_fma_f32 v[10:11], v[10:11], v[234:235], v[94:95]
	ds_read_b128 v[232:235], v42 offset:7424
	s_waitcnt lgkmcnt(6)
	v_pk_mul_f32 v[88:89], v[12:13], v[220:221]
	v_pk_fma_f32 v[88:89], v[10:11], v[222:223], v[88:89]
	v_add_f32_e32 v90, v88, v89
	v_pk_mul_f32 v[92:93], v[108:109], v[236:237] op_sel_hi:[0,1]
	v_pk_mul_f32 v[94:95], v[108:109], v[238:239] op_sel_hi:[0,1]
	v_add_f32_dpp v90, v90, v90 row_ror:8 row_mask:0xf bank_mask:0xf bound_ctrl:1
	ds_read_b128 v[220:223], v42 offset:19968
	ds_read_b128 v[236:239], v42 offset:11776
	v_add_f32_dpp v90, v90, v90 row_ror:4 row_mask:0xf bank_mask:0xf bound_ctrl:1
	v_pk_mul_f32 v[104:105], v[12:13], v[104:105]
	v_pk_fma_f32 v[104:105], v[10:11], v[106:107], v[104:105]
	v_add_f32_dpp v90, v90, v90 row_ror:2 row_mask:0xf bank_mask:0xf bound_ctrl:1
	v_add_f32_e32 v200, v104, v105
	ds_read_b128 v[104:107], v42 offset:3328
	v_add_f32_dpp v90, v90, v90 row_ror:1 row_mask:0xf bank_mask:0xf bound_ctrl:1
	v_pk_fma_f32 v[92:93], v[90:91], v[244:245], v[92:93] op_sel_hi:[0,1,1]
	v_pk_fma_f32 v[94:95], v[90:91], v[246:247], v[94:95] op_sel_hi:[0,1,1]
	ds_read_b128 v[244:247], v42 offset:24064
	v_pk_fma_f32 v[12:13], v[12:13], v[228:229], v[92:93]
	v_pk_fma_f32 v[10:11], v[10:11], v[230:231], v[94:95]
	ds_read_b128 v[228:231], v42 offset:7680
	s_waitcnt lgkmcnt(5)
	v_pk_mul_f32 v[88:89], v[12:13], v[224:225]
	v_pk_fma_f32 v[88:89], v[10:11], v[226:227], v[88:89]
	v_add_f32_e32 v90, v88, v89
	v_pk_mul_f32 v[92:93], v[108:109], v[240:241] op_sel:[1,0] op_sel_hi:[1,1]
	v_pk_mul_f32 v[94:95], v[108:109], v[242:243] op_sel:[1,0] op_sel_hi:[1,1]
	v_add_f32_dpp v90, v90, v90 row_ror:8 row_mask:0xf bank_mask:0xf bound_ctrl:1
	ds_read_b128 v[224:227], v42 offset:20224
	ds_read_b128 v[240:243], v42 offset:12032
	v_add_f32_dpp v90, v90, v90 row_ror:4 row_mask:0xf bank_mask:0xf bound_ctrl:1
	v_pk_mul_f32 v[100:101], v[12:13], v[100:101]
	v_pk_fma_f32 v[100:101], v[10:11], v[102:103], v[100:101]
	v_add_f32_dpp v90, v90, v90 row_ror:2 row_mask:0xf bank_mask:0xf bound_ctrl:1
	v_add_f32_e32 v75, v100, v101
	ds_read_b128 v[100:103], v42 offset:3584
	v_add_f32_dpp v90, v90, v90 row_ror:1 row_mask:0xf bank_mask:0xf bound_ctrl:1
	v_pk_fma_f32 v[92:93], v[90:91], v[248:249], v[92:93] op_sel_hi:[0,1,1]
	v_pk_fma_f32 v[94:95], v[90:91], v[250:251], v[94:95] op_sel_hi:[0,1,1]
	ds_read_b128 v[248:251], v42 offset:24320
	v_pk_fma_f32 v[12:13], v[12:13], v[232:233], v[92:93]
	v_pk_fma_f32 v[10:11], v[10:11], v[234:235], v[94:95]
	ds_read_b128 v[232:235], v42 offset:7936
	s_waitcnt lgkmcnt(5)
	v_pk_mul_f32 v[88:89], v[12:13], v[220:221]
	v_pk_fma_f32 v[88:89], v[10:11], v[222:223], v[88:89]
	v_add_f32_e32 v90, v88, v89
	v_pk_mul_f32 v[92:93], v[110:111], v[236:237] op_sel_hi:[0,1]
	v_pk_mul_f32 v[94:95], v[110:111], v[238:239] op_sel_hi:[0,1]
	v_add_f32_dpp v90, v90, v90 row_ror:8 row_mask:0xf bank_mask:0xf bound_ctrl:1
	s_nop 1
	v_add_f32_dpp v90, v90, v90 row_ror:4 row_mask:0xf bank_mask:0xf bound_ctrl:1
	v_pk_mul_f32 v[104:105], v[12:13], v[104:105]
	v_pk_fma_f32 v[104:105], v[10:11], v[106:107], v[104:105]
	v_add_f32_dpp v90, v90, v90 row_ror:2 row_mask:0xf bank_mask:0xf bound_ctrl:1
	v_add_f32_e32 v80, v104, v105
	ds_read_b128 v[104:107], v42 offset:3840
	v_add_f32_dpp v90, v90, v90 row_ror:1 row_mask:0xf bank_mask:0xf bound_ctrl:1
	v_pk_fma_f32 v[92:93], v[90:91], v[244:245], v[92:93] op_sel_hi:[0,1,1]
	v_pk_fma_f32 v[94:95], v[90:91], v[246:247], v[94:95] op_sel_hi:[0,1,1]
	v_pk_fma_f32 v[12:13], v[12:13], v[228:229], v[92:93]
	v_pk_fma_f32 v[10:11], v[10:11], v[230:231], v[94:95]
	s_waitcnt lgkmcnt(1)
	v_pk_mul_f32 v[88:89], v[12:13], v[224:225]
	v_pk_fma_f32 v[88:89], v[10:11], v[226:227], v[88:89]
	v_add_f32_e32 v90, v88, v89
	v_pk_mul_f32 v[92:93], v[110:111], v[240:241] op_sel:[1,0] op_sel_hi:[1,1]
	v_pk_mul_f32 v[94:95], v[110:111], v[242:243] op_sel:[1,0] op_sel_hi:[1,1]
	v_add_f32_dpp v90, v90, v90 row_ror:8 row_mask:0xf bank_mask:0xf bound_ctrl:1
	s_nop 1
	v_add_f32_dpp v90, v90, v90 row_ror:4 row_mask:0xf bank_mask:0xf bound_ctrl:1
	v_pk_mul_f32 v[100:101], v[12:13], v[100:101]
	v_pk_fma_f32 v[100:101], v[10:11], v[102:103], v[100:101]
	v_add_f32_dpp v90, v90, v90 row_ror:2 row_mask:0xf bank_mask:0xf bound_ctrl:1
	v_add_f32_e32 v81, v100, v101
	s_nop 0
	v_add_f32_dpp v90, v90, v90 row_ror:1 row_mask:0xf bank_mask:0xf bound_ctrl:1
	v_pk_fma_f32 v[92:93], v[90:91], v[248:249], v[92:93] op_sel_hi:[0,1,1]
	v_pk_fma_f32 v[94:95], v[90:91], v[250:251], v[94:95] op_sel_hi:[0,1,1]
	v_pk_fma_f32 v[12:13], v[12:13], v[232:233], v[92:93]
	v_pk_fma_f32 v[10:11], v[10:11], v[234:235], v[94:95]
	s_waitcnt lgkmcnt(0)
	v_pk_mul_f32 v[104:105], v[12:13], v[104:105]
	v_pk_fma_f32 v[104:105], v[10:11], v[106:107], v[104:105]
	v_add_f32_dpp v96, v96, v96 row_mirror row_mask:0xf bank_mask:0x3
	v_add_f32_dpp v96, v187, v187 row_mirror row_mask:0xf bank_mask:0xc
	v_add_f32_e32 v82, v104, v105
	v_add_f32_dpp v97, v97, v97 row_mirror row_mask:0xf bank_mask:0x3
	v_add_f32_dpp v97, v190, v190 row_mirror row_mask:0xf bank_mask:0xc
	v_add_f32_dpp v98, v98, v98 row_mirror row_mask:0xf bank_mask:0x3
	v_add_f32_dpp v98, v191, v191 row_mirror row_mask:0xf bank_mask:0xc
	v_add_f32_dpp v99, v99, v99 row_mirror row_mask:0xf bank_mask:0x3
	v_add_f32_dpp v99, v200, v200 row_mirror row_mask:0xf bank_mask:0xc
	v_add_f32_dpp v87, v87, v87 row_mirror row_mask:0xf bank_mask:0x3
	v_add_f32_dpp v87, v75, v75 row_mirror row_mask:0xf bank_mask:0xc
	v_add_f32_dpp v217, v217, v217 row_mirror row_mask:0xf bank_mask:0x3
	v_add_f32_dpp v217, v80, v80 row_mirror row_mask:0xf bank_mask:0xc
	v_add_f32_dpp v218, v218, v218 row_mirror row_mask:0xf bank_mask:0x3
	v_add_f32_dpp v218, v81, v81 row_mirror row_mask:0xf bank_mask:0xc
	v_add_f32_dpp v219, v219, v219 row_mirror row_mask:0xf bank_mask:0x3
	v_add_f32_dpp v219, v82, v82 row_mirror row_mask:0xf bank_mask:0xc
	v_add_f32_dpp v96, v96, v96 row_half_mirror row_mask:0xf bank_mask:0x5
	v_add_f32_dpp v96, v87, v87 row_half_mirror row_mask:0xf bank_mask:0xa
	v_add_f32_dpp v97, v97, v97 row_half_mirror row_mask:0xf bank_mask:0x5
	v_add_f32_dpp v97, v217, v217 row_half_mirror row_mask:0xf bank_mask:0xa
	v_add_f32_dpp v98, v98, v98 row_half_mirror row_mask:0xf bank_mask:0x5
	v_add_f32_dpp v98, v218, v218 row_half_mirror row_mask:0xf bank_mask:0xa
	v_add_f32_dpp v99, v99, v99 row_half_mirror row_mask:0xf bank_mask:0x5
	v_add_f32_dpp v99, v219, v219 row_half_mirror row_mask:0xf bank_mask:0xa
	s_mov_b32 vcc_lo, 0xcccccccc
	s_mov_b32 vcc_hi, 0xcccccccc
	v_cndmask_b32_e32 v187, v96, v98, vcc
	v_cndmask_b32_e32 v190, v98, v96, vcc
	v_cndmask_b32_e32 v200, v99, v97, vcc
	v_cndmask_b32_e32 v191, v97, v99, vcc
	v_add_f32_dpp v75, v190, v187 quad_perm:[2,3,0,1] row_mask:0xf bank_mask:0xf bound_ctrl:1
	v_add_f32_dpp v80, v200, v191 quad_perm:[2,3,0,1] row_mask:0xf bank_mask:0xf bound_ctrl:1
	s_mov_b32 vcc_lo, 0xaaaaaaaa
	s_mov_b32 vcc_hi, 0xaaaaaaaa
	v_cndmask_b32_e32 v81, v75, v80, vcc
	v_cndmask_b32_e32 v82, v80, v75, vcc
	s_nop 1
	v_add_f32_dpp v87, v82, v81 quad_perm:[1,0,3,2] row_mask:0xf bank_mask:0xf bound_ctrl:1
	s_waitcnt vmcnt(7)
	v_cmp_gt_i32_e32 vcc, 0, v8
	v_cmp_gt_i32_e64 s[38:39], -2, v8
	v_cmp_gt_i32_e64 s[40:41], -3, v8
	v_cmp_gt_i32_e64 s[42:43], 0, v14
	v_cmp_gt_i32_e64 s[44:45], -2, v14
	v_cmp_gt_i32_e64 s[46:47], 1, v8
	v_cmp_gt_i32_e64 s[48:49], -1, v8
	v_cmp_gt_i32_e64 s[52:53], -1, v14
	v_lshl_or_b32 v8, s5, 4, v31
	v_cndmask_b32_e64 v82, v73, 0, s[42:43]
	v_cndmask_b32_e64 v81, v76, 0, s[42:43]
	v_cndmask_b32_e64 v76, v77, 0, s[52:53]
	v_cndmask_b32_e64 v77, v84, 0, s[52:53]
	v_cndmask_b32_e64 v73, v85, 0, s[44:45]
	v_or_b32_e32 v84, s56, v8
	v_mov_b32_e32 v85, s57
	v_cmp_gt_i32_e64 s[50:51], 1, v14
	v_cmp_gt_i32_e64 s[54:55], -3, v14
	v_lshlrev_b64 v[84:85], 10, v[84:85]
	s_add_i32 s5, s4, 2
	v_cndmask_b32_e64 v89, v59, 0, vcc
	v_cndmask_b32_e64 v88, v60, 0, vcc
	v_cndmask_b32_e64 v60, v67, 0, s[38:39]
	v_cndmask_b32_e64 v59, v68, 0, s[40:41]
	v_cndmask_b32_e64 v64, v64, 0, s[38:39]
	v_cndmask_b32_e64 v75, v69, 0, s[42:43]
	v_cndmask_b32_e64 v69, v78, 0, s[44:45]
	v_cndmask_b32_e64 v67, v57, 0, s[46:47]
	v_cndmask_b32_e64 v57, v62, 0, s[48:49]
	v_cndmask_b32_e64 v62, v55, 0, s[46:47]
	v_cndmask_b32_e64 v61, v61, 0, s[48:49]
	v_cndmask_b32_e64 v55, v66, 0, s[40:41]
	v_cndmask_b32_e64 v78, v72, 0, s[50:51]
	v_cndmask_b32_e64 v74, v74, 0, s[52:53]
	s_waitcnt vmcnt(5)
	v_cndmask_b32_e64 v14, v79, 0, s[54:55]
	v_cndmask_b32_e64 v66, v54, 0, s[46:47]
	v_cndmask_b32_e64 v68, v56, 0, vcc
	v_cndmask_b32_e64 v58, v58, 0, s[48:49]
	v_cndmask_b32_e64 v56, v63, 0, s[38:39]
	v_cndmask_b32_e64 v54, v65, 0, s[40:41]
	v_cndmask_b32_e64 v80, v70, 0, s[50:51]
	v_cndmask_b32_e64 v79, v71, 0, s[50:51]
	v_cndmask_b32_e64 v72, v83, 0, s[44:45]
	v_cndmask_b32_e64 v70, v0, 0, s[54:55]
	s_waitcnt vmcnt(4)
	v_cndmask_b32_e64 v71, v86, 0, s[54:55]
	v_cvt_pk_bf16_f32 v0, v87, s0
	v_lshl_add_u64 v[84:85], v[6:7], 0, v[84:85]
	s_cmpk_lt_u32 s4, 0xfe
	s_mov_b32 s4, s5
	global_store_short v[84:85], v0, off
	s_cbranch_scc1 .LBB0_334
	s_setprio 0
	v_mov_b32_e32 v0, v133
	s_barrier
	s_nop 0
	v_cmp_eq_u32_e32 vcc, 0, v0
	s_and_saveexec_b64 s[4:5], vcc
	s_cbranch_execnz .LBB0_329
	s_branch .LBB0_332
